# EpiRes (FOXOUT/DOWN0/HGOUT): second residual batch loaded right behind the first into free VGPRs, copied at the original load sites
# baseline (speedup 1.0000x reference)
.LBB0_741:
	ds_read_b128 v[128:131], v187
	ds_read_b128 v[132:135], v187 offset:1024
	ds_read_b128 v[136:139], v187 offset:2048
	ds_read_b128 v[140:143], v187 offset:3072
	ds_read_b128 v[144:147], v188
	ds_read_b128 v[148:151], v188 offset:1024
	ds_read_b128 v[168:171], v188 offset:2048
	ds_read_b128 v[172:175], v188 offset:3072
	s_add_u32 s58, s52, 0xfffc0080
	s_addc_u32 s59, s53, -1
	s_cmp_eq_u32 s83, 12
	s_cselect_b32 s61, s6, s59
	s_cselect_b32 s60, s11, s58
	s_cselect_b32 s59, s13, s82
	s_cselect_b32 s58, s80, s81
	v_lshl_add_u64 v[216:217], s[52:53], 0, v[160:161]
	s_add_i32 m0, s62, 0xc000
	ds_read_b128 v[176:179], v189
	ds_read_b128 v[180:183], v189 offset:1024
	ds_read_b128 v[192:195], v189 offset:2048
	ds_read_b128 v[196:199], v189 offset:3072
	ds_read_b128 v[200:203], v189 offset:4096
	ds_read_b128 v[204:207], v189 offset:5120
	ds_read_b128 v[208:211], v189 offset:6144
	ds_read_b128 v[212:215], v189 offset:7168
	global_load_lds_dwordx4 v[216:217], off
	v_lshl_add_u64 v[216:217], s[52:53], 0, v[162:163]
	s_add_i32 m0, s62, 0xe000
	s_nop 0
	global_load_lds_dwordx4 v[216:217], off
	s_waitcnt vmcnt(8)
	s_waitcnt lgkmcnt(0)
	s_barrier
	s_setprio 1
	s_waitcnt lgkmcnt(0)
	v_mfma_f32_16x16x32_bf16 v[124:127], v[128:131], v[176:179], v[124:127]
	v_mfma_f32_16x16x32_bf16 v[120:123], v[136:139], v[176:179], v[120:123]
	v_mfma_f32_16x16x32_bf16 v[108:111], v[128:131], v[192:195], v[108:111]
	v_mfma_f32_16x16x32_bf16 v[104:107], v[136:139], v[192:195], v[104:107]
	v_mfma_f32_16x16x32_bf16 v[92:95], v[128:131], v[200:203], v[92:95]
	v_mfma_f32_16x16x32_bf16 v[88:91], v[136:139], v[200:203], v[88:91]
	v_mfma_f32_16x16x32_bf16 v[76:79], v[128:131], v[208:211], v[76:79]
	v_mfma_f32_16x16x32_bf16 v[72:75], v[136:139], v[208:211], v[72:75]
	v_mfma_f32_16x16x32_bf16 v[124:127], v[132:135], v[180:183], v[124:127]
	v_mfma_f32_16x16x32_bf16 v[120:123], v[140:143], v[180:183], v[120:123]
	v_mfma_f32_16x16x32_bf16 v[108:111], v[132:135], v[196:199], v[108:111]
	v_mfma_f32_16x16x32_bf16 v[104:107], v[140:143], v[196:199], v[104:107]
	v_mfma_f32_16x16x32_bf16 v[92:95], v[132:135], v[204:207], v[92:95]
	v_mfma_f32_16x16x32_bf16 v[88:91], v[140:143], v[204:207], v[88:91]
	v_mfma_f32_16x16x32_bf16 v[76:79], v[132:135], v[212:215], v[76:79]
	v_mfma_f32_16x16x32_bf16 v[72:75], v[140:143], v[212:215], v[72:75]
	s_setprio 0
	s_setprio 1
	v_mfma_f32_16x16x32_bf16 v[116:119], v[144:147], v[176:179], v[116:119]
	v_mfma_f32_16x16x32_bf16 v[112:115], v[168:171], v[176:179], v[112:115]
	v_mfma_f32_16x16x32_bf16 v[100:103], v[144:147], v[192:195], v[100:103]
	v_mfma_f32_16x16x32_bf16 v[96:99], v[168:171], v[192:195], v[96:99]
	v_mfma_f32_16x16x32_bf16 v[84:87], v[144:147], v[200:203], v[84:87]
	v_mfma_f32_16x16x32_bf16 v[80:83], v[168:171], v[200:203], v[80:83]
	v_mfma_f32_16x16x32_bf16 v[68:71], v[144:147], v[208:211], v[68:71]
	v_mfma_f32_16x16x32_bf16 v[64:67], v[168:171], v[208:211], v[64:67]
	v_mfma_f32_16x16x32_bf16 v[116:119], v[148:151], v[180:183], v[116:119]
	v_mfma_f32_16x16x32_bf16 v[112:115], v[172:175], v[180:183], v[112:115]
	v_mfma_f32_16x16x32_bf16 v[100:103], v[148:151], v[196:199], v[100:103]
	v_mfma_f32_16x16x32_bf16 v[96:99], v[172:175], v[196:199], v[96:99]
	v_mfma_f32_16x16x32_bf16 v[84:87], v[148:151], v[204:207], v[84:87]
	v_mfma_f32_16x16x32_bf16 v[80:83], v[172:175], v[204:207], v[80:83]
	v_mfma_f32_16x16x32_bf16 v[68:71], v[148:151], v[212:215], v[68:71]
	v_mfma_f32_16x16x32_bf16 v[64:67], v[172:175], v[212:215], v[64:67]
	s_setprio 0
	s_barrier
	s_add_i32 s84, s71, s57
	v_lshl_add_u64 v[216:217], s[58:59], 0, v[154:155]
	s_mov_b32 m0, s84
	ds_read_b128 v[176:179], v189 offset:16384
	ds_read_b128 v[180:183], v189 offset:17408
	ds_read_b128 v[192:195], v189 offset:18432
	ds_read_b128 v[196:199], v189 offset:19456
	ds_read_b128 v[200:203], v189 offset:20480
	ds_read_b128 v[204:207], v189 offset:21504
	ds_read_b128 v[208:211], v189 offset:22528
	ds_read_b128 v[212:215], v189 offset:23552
	global_load_lds_dwordx4 v[216:217], off
	s_add_i32 m0, s84, 0x2000
	s_add_u32 s84, s58, 0x40000
	v_lshl_add_u64 v[218:219], s[58:59], 0, v[158:159]
	s_addc_u32 s85, s59, 0
	s_add_i32 s86, s72, s57
	global_load_lds_dwordx4 v[218:219], off
	v_lshl_add_u64 v[220:221], s[84:85], 0, v[154:155]
	s_mov_b32 m0, s86
	v_lshl_add_u64 v[222:223], s[60:61], 0, v[156:157]
	global_load_lds_dwordx4 v[220:221], off
	v_lshl_add_u64 v[220:221], s[84:85], 0, v[158:159]
	s_add_i32 m0, s86, 0x2000
	s_nop 0
	global_load_lds_dwordx4 v[220:221], off
	v_lshl_add_u64 v[220:221], s[60:61], 0, v[152:153]
	s_mov_b32 m0, s62
	s_nop 0
	global_load_lds_dwordx4 v[220:221], off
	s_mov_b32 m0, s63
	s_nop 0
	global_load_lds_dwordx4 v[222:223], off
	s_waitcnt vmcnt(8)
	s_waitcnt lgkmcnt(0)
	s_barrier
	s_setprio 1
	s_waitcnt lgkmcnt(0)
	v_mfma_f32_16x16x32_bf16 v[60:63], v[128:131], v[176:179], v[60:63]
	v_mfma_f32_16x16x32_bf16 v[56:59], v[136:139], v[176:179], v[56:59]
	v_mfma_f32_16x16x32_bf16 v[44:47], v[128:131], v[192:195], v[44:47]
	v_mfma_f32_16x16x32_bf16 v[40:43], v[136:139], v[192:195], v[40:43]
	v_mfma_f32_16x16x32_bf16 v[28:31], v[128:131], v[200:203], v[28:31]
	v_mfma_f32_16x16x32_bf16 v[24:27], v[136:139], v[200:203], v[24:27]
	v_mfma_f32_16x16x32_bf16 v[12:15], v[128:131], v[208:211], v[12:15]
	v_mfma_f32_16x16x32_bf16 v[8:11], v[136:139], v[208:211], v[8:11]
	v_mfma_f32_16x16x32_bf16 v[60:63], v[132:135], v[180:183], v[60:63]
	v_mfma_f32_16x16x32_bf16 v[56:59], v[140:143], v[180:183], v[56:59]
	v_mfma_f32_16x16x32_bf16 v[44:47], v[132:135], v[196:199], v[44:47]
	v_mfma_f32_16x16x32_bf16 v[40:43], v[140:143], v[196:199], v[40:43]
	v_mfma_f32_16x16x32_bf16 v[28:31], v[132:135], v[204:207], v[28:31]
	v_mfma_f32_16x16x32_bf16 v[24:27], v[140:143], v[204:207], v[24:27]
	v_mfma_f32_16x16x32_bf16 v[12:15], v[132:135], v[212:215], v[12:15]
	v_mfma_f32_16x16x32_bf16 v[8:11], v[140:143], v[212:215], v[8:11]
	s_setprio 0
	s_setprio 1
	v_mfma_f32_16x16x32_bf16 v[52:55], v[144:147], v[176:179], v[52:55]
	v_mfma_f32_16x16x32_bf16 v[48:51], v[168:171], v[176:179], v[48:51]
	v_mfma_f32_16x16x32_bf16 v[36:39], v[144:147], v[192:195], v[36:39]
	v_mfma_f32_16x16x32_bf16 v[32:35], v[168:171], v[192:195], v[32:35]
	v_mfma_f32_16x16x32_bf16 v[20:23], v[144:147], v[200:203], v[20:23]
	v_mfma_f32_16x16x32_bf16 v[16:19], v[168:171], v[200:203], v[16:19]
	v_mfma_f32_16x16x32_bf16 v[4:7], v[144:147], v[208:211], v[4:7]
	v_mfma_f32_16x16x32_bf16 v[0:3], v[168:171], v[208:211], v[0:3]
	v_mfma_f32_16x16x32_bf16 v[52:55], v[148:151], v[180:183], v[52:55]
	v_mfma_f32_16x16x32_bf16 v[48:51], v[172:175], v[180:183], v[48:51]
	v_mfma_f32_16x16x32_bf16 v[36:39], v[148:151], v[196:199], v[36:39]
	v_mfma_f32_16x16x32_bf16 v[32:35], v[172:175], v[196:199], v[32:35]
	v_mfma_f32_16x16x32_bf16 v[20:23], v[148:151], v[204:207], v[20:23]
	v_mfma_f32_16x16x32_bf16 v[16:19], v[172:175], v[204:207], v[16:19]
	v_mfma_f32_16x16x32_bf16 v[4:7], v[148:151], v[212:215], v[4:7]
	v_mfma_f32_16x16x32_bf16 v[0:3], v[172:175], v[212:215], v[0:3]
	s_setprio 0
	s_barrier
	s_add_i32 s84, 0, 0x18000
	s_add_i32 s85, 0, 0x1c000
	v_add_u32_e32 v140, s84, v185
	v_add_u32_e32 v172, s85, v185
	ds_read_b128 v[128:131], v140
	ds_read_b128 v[132:135], v140 offset:1024
	ds_read_b128 v[136:139], v140 offset:2048
	ds_read_b128 v[140:143], v140 offset:3072
	ds_read_b128 v[144:147], v172
	ds_read_b128 v[148:151], v172 offset:1024
	ds_read_b128 v[168:171], v172 offset:2048
	ds_read_b128 v[172:175], v172 offset:3072
	s_add_u32 s60, s60, 0x40000
	s_addc_u32 s61, s61, 0
	s_mov_b32 m0, s64
	v_lshl_add_u64 v[224:225], s[60:61], 0, v[152:153]
	ds_read_b128 v[176:179], v189 offset:32768
	ds_read_b128 v[180:183], v189 offset:33792
	ds_read_b128 v[192:195], v189 offset:34816
	ds_read_b128 v[196:199], v189 offset:35840
	ds_read_b128 v[200:203], v189 offset:36864
	ds_read_b128 v[204:207], v189 offset:37888
	ds_read_b128 v[208:211], v189 offset:38912
	ds_read_b128 v[212:215], v189 offset:39936
	global_load_lds_dwordx4 v[224:225], off
	v_lshl_add_u64 v[224:225], s[60:61], 0, v[156:157]
	s_mov_b32 m0, s65
	s_nop 0
	global_load_lds_dwordx4 v[224:225], off
	s_waitcnt vmcnt(8)
	s_waitcnt lgkmcnt(0)
	s_barrier
	s_setprio 1
	s_waitcnt lgkmcnt(0)
	v_mfma_f32_16x16x32_bf16 v[124:127], v[128:131], v[176:179], v[124:127]
	v_mfma_f32_16x16x32_bf16 v[120:123], v[136:139], v[176:179], v[120:123]
	v_mfma_f32_16x16x32_bf16 v[108:111], v[128:131], v[192:195], v[108:111]
	v_mfma_f32_16x16x32_bf16 v[104:107], v[136:139], v[192:195], v[104:107]
	v_mfma_f32_16x16x32_bf16 v[92:95], v[128:131], v[200:203], v[92:95]
	v_mfma_f32_16x16x32_bf16 v[88:91], v[136:139], v[200:203], v[88:91]
	v_mfma_f32_16x16x32_bf16 v[76:79], v[128:131], v[208:211], v[76:79]
	v_mfma_f32_16x16x32_bf16 v[72:75], v[136:139], v[208:211], v[72:75]
	v_mfma_f32_16x16x32_bf16 v[124:127], v[132:135], v[180:183], v[124:127]
	v_mfma_f32_16x16x32_bf16 v[120:123], v[140:143], v[180:183], v[120:123]
	v_mfma_f32_16x16x32_bf16 v[108:111], v[132:135], v[196:199], v[108:111]
	v_mfma_f32_16x16x32_bf16 v[104:107], v[140:143], v[196:199], v[104:107]
	v_mfma_f32_16x16x32_bf16 v[92:95], v[132:135], v[204:207], v[92:95]
	v_mfma_f32_16x16x32_bf16 v[88:91], v[140:143], v[204:207], v[88:91]
	v_mfma_f32_16x16x32_bf16 v[76:79], v[132:135], v[212:215], v[76:79]
	v_mfma_f32_16x16x32_bf16 v[72:75], v[140:143], v[212:215], v[72:75]
	s_setprio 0
	s_setprio 1
	v_mfma_f32_16x16x32_bf16 v[116:119], v[144:147], v[176:179], v[116:119]
	v_mfma_f32_16x16x32_bf16 v[112:115], v[168:171], v[176:179], v[112:115]
	v_mfma_f32_16x16x32_bf16 v[100:103], v[144:147], v[192:195], v[100:103]
	v_mfma_f32_16x16x32_bf16 v[96:99], v[168:171], v[192:195], v[96:99]
	v_mfma_f32_16x16x32_bf16 v[84:87], v[144:147], v[200:203], v[84:87]
	v_mfma_f32_16x16x32_bf16 v[80:83], v[168:171], v[200:203], v[80:83]
	v_mfma_f32_16x16x32_bf16 v[68:71], v[144:147], v[208:211], v[68:71]
	v_mfma_f32_16x16x32_bf16 v[64:67], v[168:171], v[208:211], v[64:67]
	v_mfma_f32_16x16x32_bf16 v[116:119], v[148:151], v[180:183], v[116:119]
	v_mfma_f32_16x16x32_bf16 v[112:115], v[172:175], v[180:183], v[112:115]
	v_mfma_f32_16x16x32_bf16 v[100:103], v[148:151], v[196:199], v[100:103]
	v_mfma_f32_16x16x32_bf16 v[96:99], v[172:175], v[196:199], v[96:99]
	v_mfma_f32_16x16x32_bf16 v[84:87], v[148:151], v[204:207], v[84:87]
	v_mfma_f32_16x16x32_bf16 v[80:83], v[172:175], v[204:207], v[80:83]
	v_mfma_f32_16x16x32_bf16 v[68:71], v[148:151], v[212:215], v[68:71]
	v_mfma_f32_16x16x32_bf16 v[64:67], v[172:175], v[212:215], v[64:67]
	s_setprio 0
	s_barrier
	s_add_i32 s60, s84, s57
	v_lshl_add_u64 v[216:217], v[216:217], 0, s[8:9]
	s_mov_b32 m0, s60
	ds_read_b128 v[176:179], v189 offset:49152
	ds_read_b128 v[180:183], v189 offset:50176
	ds_read_b128 v[192:195], v189 offset:51200
	ds_read_b128 v[196:199], v189 offset:52224
	ds_read_b128 v[200:203], v189 offset:53248
	ds_read_b128 v[204:207], v189 offset:54272
	ds_read_b128 v[208:211], v189 offset:55296
	ds_read_b128 v[212:215], v189 offset:56320
	global_load_lds_dwordx4 v[216:217], off
	s_add_i32 m0, s60, 0x2000
	s_add_u32 s58, s58, 0x40080
	v_lshl_add_u64 v[216:217], v[218:219], 0, s[8:9]
	s_addc_u32 s59, s59, 0
	s_add_i32 s60, s85, s57
	global_load_lds_dwordx4 v[216:217], off
	v_lshl_add_u64 v[216:217], s[58:59], 0, v[154:155]
	s_mov_b32 m0, s60
	s_nop 0
	global_load_lds_dwordx4 v[216:217], off
	v_lshl_add_u64 v[216:217], s[58:59], 0, v[158:159]
	s_add_i32 m0, s60, 0x2000
	s_nop 0
	global_load_lds_dwordx4 v[216:217], off
	v_lshl_add_u64 v[216:217], v[220:221], 0, s[8:9]
	s_mov_b32 m0, s67
	s_nop 0
	global_load_lds_dwordx4 v[216:217], off
	v_lshl_add_u64 v[216:217], v[222:223], 0, s[8:9]
	s_mov_b32 m0, s68
	s_nop 0
	global_load_lds_dwordx4 v[216:217], off
	s_waitcnt vmcnt(8)
	s_waitcnt lgkmcnt(0)
	s_barrier
	s_setprio 1
	s_waitcnt lgkmcnt(0)
	v_mfma_f32_16x16x32_bf16 v[60:63], v[128:131], v[176:179], v[60:63]
	v_mfma_f32_16x16x32_bf16 v[56:59], v[136:139], v[176:179], v[56:59]
	v_mfma_f32_16x16x32_bf16 v[44:47], v[128:131], v[192:195], v[44:47]
	v_mfma_f32_16x16x32_bf16 v[40:43], v[136:139], v[192:195], v[40:43]
	v_mfma_f32_16x16x32_bf16 v[28:31], v[128:131], v[200:203], v[28:31]
	v_mfma_f32_16x16x32_bf16 v[24:27], v[136:139], v[200:203], v[24:27]
	v_mfma_f32_16x16x32_bf16 v[12:15], v[128:131], v[208:211], v[12:15]
	v_mfma_f32_16x16x32_bf16 v[8:11], v[136:139], v[208:211], v[8:11]
	v_mfma_f32_16x16x32_bf16 v[60:63], v[132:135], v[180:183], v[60:63]
	v_mfma_f32_16x16x32_bf16 v[56:59], v[140:143], v[180:183], v[56:59]
	v_mfma_f32_16x16x32_bf16 v[44:47], v[132:135], v[196:199], v[44:47]
	v_mfma_f32_16x16x32_bf16 v[40:43], v[140:143], v[196:199], v[40:43]
	v_mfma_f32_16x16x32_bf16 v[28:31], v[132:135], v[204:207], v[28:31]
	v_mfma_f32_16x16x32_bf16 v[24:27], v[140:143], v[204:207], v[24:27]
	v_mfma_f32_16x16x32_bf16 v[12:15], v[132:135], v[212:215], v[12:15]
	v_mfma_f32_16x16x32_bf16 v[8:11], v[140:143], v[212:215], v[8:11]
	s_setprio 0
	s_setprio 1
	v_mfma_f32_16x16x32_bf16 v[52:55], v[144:147], v[176:179], v[52:55]
	v_mfma_f32_16x16x32_bf16 v[48:51], v[168:171], v[176:179], v[48:51]
	v_mfma_f32_16x16x32_bf16 v[36:39], v[144:147], v[192:195], v[36:39]
	v_mfma_f32_16x16x32_bf16 v[32:35], v[168:171], v[192:195], v[32:35]
	v_mfma_f32_16x16x32_bf16 v[20:23], v[144:147], v[200:203], v[20:23]
	v_mfma_f32_16x16x32_bf16 v[16:19], v[168:171], v[200:203], v[16:19]
	v_mfma_f32_16x16x32_bf16 v[4:7], v[144:147], v[208:211], v[4:7]
	v_mfma_f32_16x16x32_bf16 v[0:3], v[168:171], v[208:211], v[0:3]
	v_mfma_f32_16x16x32_bf16 v[52:55], v[148:151], v[180:183], v[52:55]
	v_mfma_f32_16x16x32_bf16 v[48:51], v[172:175], v[180:183], v[48:51]
	v_mfma_f32_16x16x32_bf16 v[36:39], v[148:151], v[196:199], v[36:39]
	v_mfma_f32_16x16x32_bf16 v[32:35], v[172:175], v[196:199], v[32:35]
	v_mfma_f32_16x16x32_bf16 v[20:23], v[148:151], v[204:207], v[20:23]
	v_mfma_f32_16x16x32_bf16 v[16:19], v[172:175], v[204:207], v[16:19]
	v_mfma_f32_16x16x32_bf16 v[4:7], v[148:151], v[212:215], v[4:7]
	v_mfma_f32_16x16x32_bf16 v[0:3], v[172:175], v[212:215], v[0:3]
	s_setprio 0
	s_barrier
	s_add_i32 s83, s83, 2
	s_add_u32 s52, s52, 0x100
	s_addc_u32 s53, s53, 0
	s_add_u32 s81, s81, 0x100
	s_addc_u32 s82, s82, 0
	s_cmp_gt_u32 s83, 13
	s_cbranch_scc0 .LBB0_741
	v_lshl_add_u32 v168, s79, 8, v184
	v_lshl_or_b32 v128, s78, 8, v186
	v_ashrrev_i32_e32 v169, 31, v168
	v_ashrrev_i32_e32 v129, 31, v128
	v_lshlrev_b64 v[130:131], 11, v[168:169]
	v_lshl_add_u64 v[130:131], s[34:35], 0, v[130:131]
	v_lshlrev_b64 v[170:171], 1, v[128:129]
	v_lshl_add_u64 v[200:201], v[130:131], 0, v[170:171]
	global_load_dwordx4 v[192:195], v[200:201], off
	global_load_dwordx4 v[196:199], v[200:201], off offset:256
	v_or_b32_e32 v180, 16, v168
	v_or_b32_e32 v176, 32, v168
	v_or_b32_e32 v172, 48, v168
	v_ashrrev_i32_e32 v181, 31, v180
	v_ashrrev_i32_e32 v177, 31, v176
	v_ashrrev_i32_e32 v173, 31, v172
	v_lshlrev_b64 v[128:129], 11, v[180:181]
	v_lshlrev_b64 v[130:131], 11, v[176:177]
	v_lshlrev_b64 v[132:133], 11, v[172:173]
	v_lshl_add_u64 v[128:129], s[34:35], 0, v[128:129]
	v_lshl_add_u64 v[130:131], s[34:35], 0, v[130:131]
	v_lshl_add_u64 v[132:133], s[34:35], 0, v[132:133]
	v_lshl_add_u64 v[182:183], v[128:129], 0, v[170:171]
	v_lshl_add_u64 v[178:179], v[130:131], 0, v[170:171]
	v_lshl_add_u64 v[174:175], v[132:133], 0, v[170:171]
	global_load_dwordx4 v[148:151], v[182:183], off
	global_load_dwordx4 v[144:147], v[182:183], off offset:256
	global_load_dwordx4 v[140:143], v[178:179], off
	global_load_dwordx4 v[136:139], v[178:179], off offset:256
	global_load_dwordx4 v[132:135], v[174:175], off
	global_load_dwordx4 v[128:131], v[174:175], off offset:256
	v_add_u32_e32 v224, 0x80, v168
	v_ashrrev_i32_e32 v225, 31, v224
	v_lshlrev_b64 v[224:225], 11, v[224:225]
	v_lshl_add_u64 v[224:225], s[34:35], 0, v[224:225]
	v_lshl_add_u64 v[212:213], v[224:225], 0, v[170:171]
	global_load_dwordx4 v[226:229], v[212:213], off
	global_load_dwordx4 v[230:233], v[212:213], off offset:256
	v_add_u32_e32 v224, 0x90, v168
	v_ashrrev_i32_e32 v225, 31, v224
	v_lshlrev_b64 v[224:225], 11, v[224:225]
	v_lshl_add_u64 v[224:225], s[34:35], 0, v[224:225]
	v_lshl_add_u64 v[214:215], v[224:225], 0, v[170:171]
	global_load_dwordx4 v[234:237], v[214:215], off
	global_load_dwordx4 v[238:241], v[214:215], off offset:256
	v_add_u32_e32 v224, 0xa0, v168
	v_ashrrev_i32_e32 v225, 31, v224
	v_lshlrev_b64 v[224:225], 11, v[224:225]
	v_lshl_add_u64 v[224:225], s[34:35], 0, v[224:225]
	v_lshl_add_u64 v[216:217], v[224:225], 0, v[170:171]
	global_load_dwordx4 v[242:245], v[216:217], off
	global_load_dwordx4 v[246:249], v[216:217], off offset:256
	v_add_u32_e32 v224, 0xb0, v168
	v_ashrrev_i32_e32 v225, 31, v224
	v_lshlrev_b64 v[224:225], 11, v[224:225]
	v_lshl_add_u64 v[224:225], s[34:35], 0, v[224:225]
	v_lshl_add_u64 v[218:219], v[224:225], 0, v[170:171]
	global_load_dwordx4 v[250:253], v[218:219], off
	global_load_dwordx4 v[220:223], v[218:219], off offset:256
	v_and_b32_e32 v202, 64, v190
	v_xor_b32_e32 v191, 16, v190
	v_add_u32_e32 v202, 64, v202
	v_xor_b32_e32 v203, 32, v190
	v_cmp_lt_i32_e32 vcc, v191, v202
	s_lshl_b32 s52, s78, 2
	s_ashr_i32 s53, s52, 31
	v_cndmask_b32_e32 v191, v190, v191, vcc
	v_cmp_lt_i32_e32 vcc, v203, v202
	v_lshlrev_b32_e32 v191, 2, v191
	s_waitcnt vmcnt(8)
	v_lshlrev_b32_e32 v202, 16, v192
	v_cndmask_b32_e32 v210, v190, v203, vcc
	v_and_b32_e32 v203, 0xffff0000, v192
	v_lshlrev_b32_e32 v192, 16, v193
	v_and_b32_e32 v193, 0xffff0000, v193
	v_lshlrev_b32_e32 v204, 16, v194
	v_and_b32_e32 v205, 0xffff0000, v194
	v_lshlrev_b32_e32 v194, 16, v195
	v_and_b32_e32 v195, 0xffff0000, v195
	v_lshlrev_b32_e32 v206, 16, v196
	v_and_b32_e32 v207, 0xffff0000, v196
	v_lshlrev_b32_e32 v196, 16, v197
	v_and_b32_e32 v197, 0xffff0000, v197
	v_lshlrev_b32_e32 v208, 16, v198
	v_and_b32_e32 v209, 0xffff0000, v198
	v_lshlrev_b32_e32 v198, 16, v199
	v_and_b32_e32 v199, 0xffff0000, v199
	v_pk_add_f32 v[126:127], v[126:127], v[192:193]
	v_pk_add_f32 v[124:125], v[124:125], v[202:203]
	v_pk_add_f32 v[122:123], v[122:123], v[194:195]
	v_pk_add_f32 v[120:121], v[120:121], v[204:205]
	v_pk_add_f32 v[118:119], v[118:119], v[196:197]
	v_pk_add_f32 v[116:117], v[116:117], v[206:207]
	v_pk_add_f32 v[192:193], v[114:115], v[198:199]
	v_pk_add_f32 v[194:195], v[112:113], v[208:209]
	v_cvt_pk_bf16_f32 v112, v124, v125
	v_cvt_pk_bf16_f32 v113, v126, v127
	v_mul_f32_e32 v114, v125, v125
	v_mul_f32_e32 v115, v127, v127
	v_mul_f32_e32 v125, v121, v121
	v_mul_f32_e32 v127, v123, v123
	v_mul_f32_e32 v196, v117, v117
	v_mul_f32_e32 v197, v119, v119
	v_mul_f32_e32 v198, v195, v195
	v_mul_f32_e32 v199, v193, v193
	v_fmac_f32_e32 v114, v124, v124
	v_fmac_f32_e32 v115, v126, v126
	v_fmac_f32_e32 v125, v120, v120
	v_fmac_f32_e32 v127, v122, v122
	v_fmac_f32_e32 v196, v116, v116
	v_fmac_f32_e32 v197, v118, v118
	v_fmac_f32_e32 v198, v194, v194
	v_fmac_f32_e32 v199, v192, v192
	v_add_f32_e32 v114, v114, v115
	v_add_f32_e32 v115, v125, v127
	v_add_f32_e32 v124, v196, v197
	v_add_f32_e32 v125, v198, v199
	v_add_f32_e32 v114, v114, v115
	v_add_f32_e32 v115, v124, v125
	v_add_f32_e32 v124, v114, v115
	ds_bpermute_b32 v125, v191, v124
	v_cvt_pk_bf16_f32 v114, v120, v121
	v_cvt_pk_bf16_f32 v115, v122, v123
	global_store_dwordx4 v[200:201], v[112:115], off
	v_cvt_pk_bf16_f32 v116, v116, v117
	v_cvt_pk_bf16_f32 v117, v118, v119
	s_waitcnt lgkmcnt(0)
	v_add_f32_e32 v113, v124, v125
	v_lshlrev_b32_e32 v112, 2, v210
	ds_bpermute_b32 v114, v112, v113
	v_cvt_pk_bf16_f32 v118, v194, v195
	v_cvt_pk_bf16_f32 v119, v192, v193
	global_store_dwordx4 v[200:201], v[116:119], off offset:256
	s_and_saveexec_b64 s[58:59], s[0:1]
	s_cbranch_execz .LBB0_744
	s_waitcnt lgkmcnt(0)
	v_add_f32_e32 v113, v113, v114
	v_lshlrev_b64 v[114:115], 6, v[168:169]
	v_lshl_add_u64 v[114:115], s[74:75], 0, v[114:115]
	v_lshl_add_u64 v[114:115], s[52:53], 2, v[114:115]
	s_lshl_b32 s6, s66, 2
	v_lshl_add_u64 v[114:115], v[114:115], 0, s[6:7]
	global_store_dword v[114:115], v113, off

.LBB0_750:
	s_or_b64 exec, exec, s[58:59]
	v_add_u32_e32 v100, 0x80, v168
	v_ashrrev_i32_e32 v101, 31, v100
	s_waitcnt lgkmcnt(0)
	v_lshlrev_b64 v[64:65], 11, v[100:101]
	v_lshl_add_u64 v[64:65], s[34:35], 0, v[64:65]
	v_lshl_add_u64 v[110:111], v[64:65], 0, v[170:171]
	s_waitcnt vmcnt(8)
	v_mov_b64_e32 v[102:103], v[226:227]
	v_mov_b64_e32 v[104:105], v[228:229]
	v_mov_b64_e32 v[106:107], v[230:231]
	v_mov_b64_e32 v[108:109], v[232:233]
	v_add_u32_e32 v96, 0x90, v168
	v_add_u32_e32 v92, 0xa0, v168
	v_add_u32_e32 v88, 0xb0, v168
	v_ashrrev_i32_e32 v97, 31, v96
	v_ashrrev_i32_e32 v93, 31, v92
	v_ashrrev_i32_e32 v89, 31, v88
	v_lshlrev_b64 v[64:65], 11, v[96:97]
	v_lshlrev_b64 v[66:67], 11, v[92:93]
	v_lshlrev_b64 v[68:69], 11, v[88:89]
	v_lshl_add_u64 v[64:65], s[34:35], 0, v[64:65]
	v_lshl_add_u64 v[66:67], s[34:35], 0, v[66:67]
	v_lshl_add_u64 v[68:69], s[34:35], 0, v[68:69]
	v_lshl_add_u64 v[98:99], v[64:65], 0, v[170:171]
	v_lshl_add_u64 v[94:95], v[66:67], 0, v[170:171]
	v_lshl_add_u64 v[90:91], v[68:69], 0, v[170:171]
	v_mov_b64_e32 v[84:85], v[234:235]
	v_mov_b64_e32 v[86:87], v[236:237]
	v_mov_b64_e32 v[80:81], v[238:239]
	v_mov_b64_e32 v[82:83], v[240:241]
	v_mov_b64_e32 v[76:77], v[242:243]
	v_mov_b64_e32 v[78:79], v[244:245]
	v_mov_b64_e32 v[72:73], v[246:247]
	v_mov_b64_e32 v[74:75], v[248:249]
	v_mov_b64_e32 v[68:69], v[250:251]
	v_mov_b64_e32 v[70:71], v[252:253]
	v_mov_b64_e32 v[64:65], v[220:221]
	v_mov_b64_e32 v[66:67], v[222:223]
	s_nop 0
	v_lshlrev_b32_e32 v114, 16, v102
	v_and_b32_e32 v115, 0xffff0000, v102
	v_lshlrev_b32_e32 v102, 16, v103
	v_and_b32_e32 v103, 0xffff0000, v103
	v_lshlrev_b32_e32 v116, 16, v104
	v_and_b32_e32 v117, 0xffff0000, v104
	v_lshlrev_b32_e32 v104, 16, v105
	v_and_b32_e32 v105, 0xffff0000, v105
	s_nop 0
	v_lshlrev_b32_e32 v118, 16, v106
	v_and_b32_e32 v119, 0xffff0000, v106
	v_lshlrev_b32_e32 v106, 16, v107
	v_and_b32_e32 v107, 0xffff0000, v107
	v_lshlrev_b32_e32 v120, 16, v108
	v_and_b32_e32 v121, 0xffff0000, v108
	v_lshlrev_b32_e32 v108, 16, v109
	v_and_b32_e32 v109, 0xffff0000, v109
	v_pk_add_f32 v[62:63], v[62:63], v[102:103]
	v_pk_add_f32 v[60:61], v[60:61], v[114:115]
	v_pk_add_f32 v[58:59], v[58:59], v[104:105]
	v_pk_add_f32 v[56:57], v[56:57], v[116:117]
	v_pk_add_f32 v[54:55], v[54:55], v[106:107]
	v_pk_add_f32 v[52:53], v[52:53], v[118:119]
	v_pk_add_f32 v[102:103], v[50:51], v[108:109]
	v_pk_add_f32 v[104:105], v[48:49], v[120:121]
	v_cvt_pk_bf16_f32 v48, v60, v61
	v_cvt_pk_bf16_f32 v49, v62, v63
	v_mul_f32_e32 v50, v61, v61
	v_mul_f32_e32 v51, v63, v63
	v_mul_f32_e32 v61, v57, v57
	v_mul_f32_e32 v63, v59, v59
	v_mul_f32_e32 v106, v53, v53
	v_mul_f32_e32 v107, v55, v55
	v_mul_f32_e32 v108, v105, v105
	v_mul_f32_e32 v109, v103, v103
	v_fmac_f32_e32 v50, v60, v60
	v_fmac_f32_e32 v51, v62, v62
	v_fmac_f32_e32 v61, v56, v56
	v_fmac_f32_e32 v63, v58, v58
	v_fmac_f32_e32 v106, v52, v52
	v_fmac_f32_e32 v107, v54, v54
	v_fmac_f32_e32 v108, v104, v104
	v_fmac_f32_e32 v109, v102, v102
	v_add_f32_e32 v50, v50, v51
	v_add_f32_e32 v51, v61, v63
	v_add_f32_e32 v60, v106, v107
	v_add_f32_e32 v61, v108, v109
	v_add_f32_e32 v50, v50, v51
	v_add_f32_e32 v51, v60, v61
	v_add_f32_e32 v60, v50, v51
	ds_bpermute_b32 v61, v191, v60
	v_cvt_pk_bf16_f32 v50, v56, v57
	v_cvt_pk_bf16_f32 v51, v58, v59
	global_store_dwordx4 v[110:111], v[48:51], off
	s_waitcnt lgkmcnt(0)
	s_nop 0
	v_add_f32_e32 v48, v60, v61
	ds_bpermute_b32 v49, v112, v48
	v_cvt_pk_bf16_f32 v50, v52, v53
	v_cvt_pk_bf16_f32 v51, v54, v55
	v_cvt_pk_bf16_f32 v52, v104, v105
	v_cvt_pk_bf16_f32 v53, v102, v103
	global_store_dwordx4 v[110:111], v[50:53], off offset:256
	s_and_saveexec_b64 s[58:59], s[0:1]
	s_cbranch_execz .LBB0_752
	s_waitcnt lgkmcnt(0)
	v_add_f32_e32 v50, v48, v49
	v_lshlrev_b64 v[48:49], 6, v[100:101]
	v_lshl_add_u64 v[48:49], s[74:75], 0, v[48:49]
	v_lshl_add_u64 v[48:49], s[52:53], 2, v[48:49]
	s_lshl_b32 s6, s66, 2
	v_lshl_add_u64 v[48:49], v[48:49], 0, s[6:7]
	global_store_dword v[48:49], v50, off
.LBB0_752:
	s_or_b64 exec, exec, s[58:59]
	s_nop 0
	v_lshlrev_b32_e32 v48, 16, v84
	s_waitcnt lgkmcnt(0)
	v_and_b32_e32 v49, 0xffff0000, v84
	v_lshlrev_b32_e32 v50, 16, v85
	v_and_b32_e32 v51, 0xffff0000, v85
	v_lshlrev_b32_e32 v52, 16, v86
	v_and_b32_e32 v53, 0xffff0000, v86
	v_lshlrev_b32_e32 v54, 16, v87
	v_and_b32_e32 v55, 0xffff0000, v87
	s_nop 0
	v_lshlrev_b32_e32 v60, 16, v82
	v_and_b32_e32 v61, 0xffff0000, v82
	v_pk_add_f32 v[46:47], v[46:47], v[50:51]
	v_pk_add_f32 v[44:45], v[44:45], v[48:49]
	v_pk_add_f32 v[48:49], v[42:43], v[54:55]
	v_pk_add_f32 v[42:43], v[40:41], v[52:53]
	v_pk_add_f32 v[52:53], v[32:33], v[60:61]
	v_mul_f32_e32 v32, v45, v45
	v_mul_f32_e32 v33, v47, v47
	v_lshlrev_b32_e32 v62, 16, v83
	v_and_b32_e32 v63, 0xffff0000, v83
	v_fmac_f32_e32 v32, v44, v44
	v_fmac_f32_e32 v33, v46, v46
	v_pk_add_f32 v[50:51], v[34:35], v[62:63]
	v_add_f32_e32 v32, v32, v33
	v_mul_f32_e32 v33, v43, v43
	v_mul_f32_e32 v34, v49, v49
	v_lshlrev_b32_e32 v56, 16, v80
	v_and_b32_e32 v57, 0xffff0000, v80
	v_lshlrev_b32_e32 v58, 16, v81
	v_and_b32_e32 v59, 0xffff0000, v81
	v_fmac_f32_e32 v33, v42, v42
	v_fmac_f32_e32 v34, v48, v48
	v_pk_add_f32 v[38:39], v[38:39], v[58:59]
	v_pk_add_f32 v[36:37], v[36:37], v[56:57]
	v_add_f32_e32 v33, v33, v34
	v_add_f32_e32 v32, v32, v33
	v_mul_f32_e32 v33, v37, v37
	v_mul_f32_e32 v34, v39, v39
	v_fmac_f32_e32 v33, v36, v36
	v_fmac_f32_e32 v34, v38, v38
	v_add_f32_e32 v33, v33, v34
	v_mul_f32_e32 v34, v53, v53
	v_mul_f32_e32 v35, v51, v51
	v_fmac_f32_e32 v34, v52, v52
	v_fmac_f32_e32 v35, v50, v50
	v_add_f32_e32 v34, v34, v35
	v_add_f32_e32 v33, v33, v34
	v_add_f32_e32 v32, v32, v33
	ds_bpermute_b32 v33, v191, v32
	v_cvt_pk_bf16_f32 v40, v44, v45
	v_cvt_pk_bf16_f32 v41, v46, v47
	v_cvt_pk_bf16_f32 v42, v42, v43
	v_cvt_pk_bf16_f32 v43, v48, v49
	s_waitcnt lgkmcnt(0)
	v_add_f32_e32 v32, v32, v33
	ds_bpermute_b32 v33, v112, v32
	v_cvt_pk_bf16_f32 v34, v36, v37
	v_cvt_pk_bf16_f32 v35, v38, v39
	v_cvt_pk_bf16_f32 v36, v52, v53
	v_cvt_pk_bf16_f32 v37, v50, v51
	global_store_dwordx4 v[98:99], v[40:43], off
	global_store_dwordx4 v[98:99], v[34:37], off offset:256
	s_and_saveexec_b64 s[58:59], s[0:1]
	s_cbranch_execz .LBB0_754
	s_waitcnt lgkmcnt(0)
	v_add_f32_e32 v34, v32, v33
	v_lshlrev_b64 v[32:33], 6, v[96:97]
	v_lshl_add_u64 v[32:33], s[74:75], 0, v[32:33]
	v_lshl_add_u64 v[32:33], s[52:53], 2, v[32:33]
	s_lshl_b32 s6, s66, 2
	v_lshl_add_u64 v[32:33], v[32:33], 0, s[6:7]
	global_store_dword v[32:33], v34, off
.LBB0_754:
	s_or_b64 exec, exec, s[58:59]
	s_nop 0
	v_lshlrev_b32_e32 v32, 16, v76
	s_waitcnt lgkmcnt(0)
	v_and_b32_e32 v33, 0xffff0000, v76
	v_lshlrev_b32_e32 v34, 16, v77
	v_and_b32_e32 v35, 0xffff0000, v77
	v_lshlrev_b32_e32 v36, 16, v78
	v_and_b32_e32 v37, 0xffff0000, v78
	v_lshlrev_b32_e32 v38, 16, v79
	v_and_b32_e32 v39, 0xffff0000, v79
	s_nop 0
	v_lshlrev_b32_e32 v44, 16, v74
	v_and_b32_e32 v45, 0xffff0000, v74
	v_pk_add_f32 v[30:31], v[30:31], v[34:35]
	v_pk_add_f32 v[28:29], v[28:29], v[32:33]
	v_pk_add_f32 v[32:33], v[26:27], v[38:39]
	v_pk_add_f32 v[26:27], v[24:25], v[36:37]
	v_pk_add_f32 v[36:37], v[16:17], v[44:45]
	v_mul_f32_e32 v16, v29, v29
	v_mul_f32_e32 v17, v31, v31
	v_lshlrev_b32_e32 v46, 16, v75
	v_and_b32_e32 v47, 0xffff0000, v75
	v_fmac_f32_e32 v16, v28, v28
	v_fmac_f32_e32 v17, v30, v30
	v_pk_add_f32 v[34:35], v[18:19], v[46:47]
	v_add_f32_e32 v16, v16, v17
	v_mul_f32_e32 v17, v27, v27
	v_mul_f32_e32 v18, v33, v33
	v_lshlrev_b32_e32 v40, 16, v72
	v_and_b32_e32 v41, 0xffff0000, v72
	v_lshlrev_b32_e32 v42, 16, v73
	v_and_b32_e32 v43, 0xffff0000, v73
	v_fmac_f32_e32 v17, v26, v26
	v_fmac_f32_e32 v18, v32, v32
	v_pk_add_f32 v[22:23], v[22:23], v[42:43]
	v_pk_add_f32 v[20:21], v[20:21], v[40:41]
	v_add_f32_e32 v17, v17, v18
	v_add_f32_e32 v16, v16, v17
	v_mul_f32_e32 v17, v21, v21
	v_mul_f32_e32 v18, v23, v23
	v_fmac_f32_e32 v17, v20, v20
	v_fmac_f32_e32 v18, v22, v22
	v_add_f32_e32 v17, v17, v18
	v_mul_f32_e32 v18, v37, v37
	v_mul_f32_e32 v19, v35, v35
	v_fmac_f32_e32 v18, v36, v36
	v_fmac_f32_e32 v19, v34, v34
	v_add_f32_e32 v18, v18, v19
	v_add_f32_e32 v17, v17, v18
	v_add_f32_e32 v16, v16, v17
	ds_bpermute_b32 v17, v191, v16
	v_cvt_pk_bf16_f32 v24, v28, v29
	v_cvt_pk_bf16_f32 v25, v30, v31
	v_cvt_pk_bf16_f32 v26, v26, v27
	v_cvt_pk_bf16_f32 v27, v32, v33
	s_waitcnt lgkmcnt(0)
	v_add_f32_e32 v16, v16, v17
	ds_bpermute_b32 v17, v112, v16
	v_cvt_pk_bf16_f32 v18, v20, v21
	v_cvt_pk_bf16_f32 v19, v22, v23
	v_cvt_pk_bf16_f32 v20, v36, v37
	v_cvt_pk_bf16_f32 v21, v34, v35
	global_store_dwordx4 v[94:95], v[24:27], off
	global_store_dwordx4 v[94:95], v[18:21], off offset:256
	s_and_saveexec_b64 s[58:59], s[0:1]
	s_cbranch_execz .LBB0_756
	s_waitcnt lgkmcnt(0)
	v_add_f32_e32 v18, v16, v17
	v_lshlrev_b64 v[16:17], 6, v[92:93]
	v_lshl_add_u64 v[16:17], s[74:75], 0, v[16:17]
	v_lshl_add_u64 v[16:17], s[52:53], 2, v[16:17]
	s_lshl_b32 s6, s66, 2
	v_lshl_add_u64 v[16:17], v[16:17], 0, s[6:7]
	global_store_dword v[16:17], v18, off
.LBB0_756:
	s_or_b64 exec, exec, s[58:59]
	s_nop 0
	v_lshlrev_b32_e32 v16, 16, v68
	s_waitcnt lgkmcnt(0)
	v_and_b32_e32 v17, 0xffff0000, v68
	v_lshlrev_b32_e32 v18, 16, v69
	v_and_b32_e32 v19, 0xffff0000, v69
	v_lshlrev_b32_e32 v20, 16, v70
	v_and_b32_e32 v21, 0xffff0000, v70
	v_lshlrev_b32_e32 v22, 16, v71
	v_and_b32_e32 v23, 0xffff0000, v71
	s_nop 0
	v_lshlrev_b32_e32 v28, 16, v66
	v_and_b32_e32 v29, 0xffff0000, v66
	v_pk_add_f32 v[14:15], v[14:15], v[18:19]
	v_pk_add_f32 v[12:13], v[12:13], v[16:17]
	v_pk_add_f32 v[16:17], v[10:11], v[22:23]
	v_pk_add_f32 v[10:11], v[8:9], v[20:21]
	v_pk_add_f32 v[20:21], v[0:1], v[28:29]
	v_mul_f32_e32 v0, v13, v13
	v_mul_f32_e32 v1, v15, v15
	v_lshlrev_b32_e32 v30, 16, v67
	v_and_b32_e32 v31, 0xffff0000, v67
	v_fmac_f32_e32 v0, v12, v12
	v_fmac_f32_e32 v1, v14, v14
	v_pk_add_f32 v[18:19], v[2:3], v[30:31]
	v_add_f32_e32 v0, v0, v1
	v_mul_f32_e32 v1, v11, v11
	v_mul_f32_e32 v2, v17, v17
	v_lshlrev_b32_e32 v24, 16, v64
	v_and_b32_e32 v25, 0xffff0000, v64
	v_lshlrev_b32_e32 v26, 16, v65
	v_and_b32_e32 v27, 0xffff0000, v65
	v_fmac_f32_e32 v1, v10, v10
	v_fmac_f32_e32 v2, v16, v16
	v_pk_add_f32 v[6:7], v[6:7], v[26:27]
	v_pk_add_f32 v[4:5], v[4:5], v[24:25]
	v_add_f32_e32 v1, v1, v2
	v_add_f32_e32 v0, v0, v1
	v_mul_f32_e32 v1, v5, v5
	v_mul_f32_e32 v2, v7, v7
	v_fmac_f32_e32 v1, v4, v4
	v_fmac_f32_e32 v2, v6, v6
	v_add_f32_e32 v1, v1, v2
	v_mul_f32_e32 v2, v21, v21
	v_mul_f32_e32 v3, v19, v19
	v_fmac_f32_e32 v2, v20, v20
	v_fmac_f32_e32 v3, v18, v18
	v_add_f32_e32 v2, v2, v3
	v_add_f32_e32 v1, v1, v2
	v_add_f32_e32 v0, v0, v1
	ds_bpermute_b32 v1, v191, v0
	v_cvt_pk_bf16_f32 v8, v12, v13
	v_cvt_pk_bf16_f32 v9, v14, v15
	v_cvt_pk_bf16_f32 v10, v10, v11
	v_cvt_pk_bf16_f32 v11, v16, v17
	s_waitcnt lgkmcnt(0)
	v_add_f32_e32 v0, v0, v1
	ds_bpermute_b32 v1, v112, v0
	v_cvt_pk_bf16_f32 v2, v4, v5
	v_cvt_pk_bf16_f32 v3, v6, v7
	v_cvt_pk_bf16_f32 v4, v20, v21
	v_cvt_pk_bf16_f32 v5, v18, v19
	global_store_dwordx4 v[90:91], v[8:11], off
	global_store_dwordx4 v[90:91], v[2:5], off offset:256
	s_and_saveexec_b64 s[58:59], s[0:1]
	s_cbranch_execz .LBB0_733
	s_waitcnt lgkmcnt(0)
	v_add_f32_e32 v2, v0, v1
	v_lshlrev_b64 v[0:1], 6, v[88:89]
	v_lshl_add_u64 v[0:1], s[74:75], 0, v[0:1]
	v_lshl_add_u64 v[0:1], s[52:53], 2, v[0:1]
	s_lshl_b32 s6, s66, 2
	v_lshl_add_u64 v[0:1], v[0:1], 0, s[6:7]
	global_store_dword v[0:1], v2, off
	s_branch .LBB0_733

.LBB0_1080:
	ds_read_b128 v[128:131], v187
	ds_read_b128 v[132:135], v187 offset:1024
	ds_read_b128 v[136:139], v187 offset:2048
	ds_read_b128 v[140:143], v187 offset:3072
	ds_read_b128 v[144:147], v188
	ds_read_b128 v[148:151], v188 offset:1024
	ds_read_b128 v[168:171], v188 offset:2048
	ds_read_b128 v[172:175], v188 offset:3072
	s_add_u32 s38, s36, 0x100
	s_addc_u32 s39, s37, 0
	s_cmp_eq_u32 s77, 40
	s_cselect_b32 s61, s5, s39
	s_cselect_b32 s60, s4, s38
	s_cselect_b32 s45, s7, s76
	s_cselect_b32 s44, s6, s73
	v_lshl_add_u64 v[216:217], s[36:37], 0, v[160:161]
	s_add_i32 m0, s54, 0xc000
	ds_read_b128 v[176:179], v189
	ds_read_b128 v[180:183], v189 offset:1024
	ds_read_b128 v[192:195], v189 offset:2048
	ds_read_b128 v[196:199], v189 offset:3072
	ds_read_b128 v[200:203], v189 offset:4096
	ds_read_b128 v[204:207], v189 offset:5120
	ds_read_b128 v[208:211], v189 offset:6144
	ds_read_b128 v[212:215], v189 offset:7168
	global_load_lds_dwordx4 v[216:217], off
	v_lshl_add_u64 v[216:217], s[36:37], 0, v[162:163]
	s_add_i32 m0, s54, 0xe000
	s_nop 0
	global_load_lds_dwordx4 v[216:217], off
	s_waitcnt vmcnt(8)
	s_waitcnt lgkmcnt(0)
	s_barrier
	s_setprio 1
	s_waitcnt lgkmcnt(0)
	v_mfma_f32_16x16x32_bf16 v[124:127], v[128:131], v[176:179], v[124:127]
	v_mfma_f32_16x16x32_bf16 v[120:123], v[136:139], v[176:179], v[120:123]
	v_mfma_f32_16x16x32_bf16 v[108:111], v[128:131], v[192:195], v[108:111]
	v_mfma_f32_16x16x32_bf16 v[104:107], v[136:139], v[192:195], v[104:107]
	v_mfma_f32_16x16x32_bf16 v[92:95], v[128:131], v[200:203], v[92:95]
	v_mfma_f32_16x16x32_bf16 v[88:91], v[136:139], v[200:203], v[88:91]
	v_mfma_f32_16x16x32_bf16 v[76:79], v[128:131], v[208:211], v[76:79]
	v_mfma_f32_16x16x32_bf16 v[72:75], v[136:139], v[208:211], v[72:75]
	v_mfma_f32_16x16x32_bf16 v[124:127], v[132:135], v[180:183], v[124:127]
	v_mfma_f32_16x16x32_bf16 v[120:123], v[140:143], v[180:183], v[120:123]
	v_mfma_f32_16x16x32_bf16 v[108:111], v[132:135], v[196:199], v[108:111]
	v_mfma_f32_16x16x32_bf16 v[104:107], v[140:143], v[196:199], v[104:107]
	v_mfma_f32_16x16x32_bf16 v[92:95], v[132:135], v[204:207], v[92:95]
	v_mfma_f32_16x16x32_bf16 v[88:91], v[140:143], v[204:207], v[88:91]
	v_mfma_f32_16x16x32_bf16 v[76:79], v[132:135], v[212:215], v[76:79]
	v_mfma_f32_16x16x32_bf16 v[72:75], v[140:143], v[212:215], v[72:75]
	s_setprio 0
	s_setprio 1
	v_mfma_f32_16x16x32_bf16 v[116:119], v[144:147], v[176:179], v[116:119]
	v_mfma_f32_16x16x32_bf16 v[112:115], v[168:171], v[176:179], v[112:115]
	v_mfma_f32_16x16x32_bf16 v[100:103], v[144:147], v[192:195], v[100:103]
	v_mfma_f32_16x16x32_bf16 v[96:99], v[168:171], v[192:195], v[96:99]
	v_mfma_f32_16x16x32_bf16 v[84:87], v[144:147], v[200:203], v[84:87]
	v_mfma_f32_16x16x32_bf16 v[80:83], v[168:171], v[200:203], v[80:83]
	v_mfma_f32_16x16x32_bf16 v[68:71], v[144:147], v[208:211], v[68:71]
	v_mfma_f32_16x16x32_bf16 v[64:67], v[168:171], v[208:211], v[64:67]
	v_mfma_f32_16x16x32_bf16 v[116:119], v[148:151], v[180:183], v[116:119]
	v_mfma_f32_16x16x32_bf16 v[112:115], v[172:175], v[180:183], v[112:115]
	v_mfma_f32_16x16x32_bf16 v[100:103], v[148:151], v[196:199], v[100:103]
	v_mfma_f32_16x16x32_bf16 v[96:99], v[172:175], v[196:199], v[96:99]
	v_mfma_f32_16x16x32_bf16 v[84:87], v[148:151], v[204:207], v[84:87]
	v_mfma_f32_16x16x32_bf16 v[80:83], v[172:175], v[204:207], v[80:83]
	v_mfma_f32_16x16x32_bf16 v[68:71], v[148:151], v[212:215], v[68:71]
	v_mfma_f32_16x16x32_bf16 v[64:67], v[172:175], v[212:215], v[64:67]
	s_setprio 0
	s_barrier
	s_add_i32 s36, s65, s53
	v_lshl_add_u64 v[216:217], s[44:45], 0, v[154:155]
	s_mov_b32 m0, s36
	ds_read_b128 v[176:179], v189 offset:16384
	ds_read_b128 v[180:183], v189 offset:17408
	ds_read_b128 v[192:195], v189 offset:18432
	ds_read_b128 v[196:199], v189 offset:19456
	ds_read_b128 v[200:203], v189 offset:20480
	ds_read_b128 v[204:207], v189 offset:21504
	ds_read_b128 v[208:211], v189 offset:22528
	ds_read_b128 v[212:215], v189 offset:23552
	global_load_lds_dwordx4 v[216:217], off
	s_add_i32 m0, s36, 0x2000
	s_add_u32 s36, s44, 0xb0000
	v_lshl_add_u64 v[218:219], s[44:45], 0, v[158:159]
	s_addc_u32 s37, s45, 0
	s_add_i32 s78, s66, s53
	global_load_lds_dwordx4 v[218:219], off
	v_lshl_add_u64 v[220:221], s[36:37], 0, v[154:155]
	s_mov_b32 m0, s78
	v_lshl_add_u64 v[222:223], s[60:61], 0, v[156:157]
	global_load_lds_dwordx4 v[220:221], off
	v_lshl_add_u64 v[220:221], s[36:37], 0, v[158:159]
	s_add_i32 m0, s78, 0x2000
	s_nop 0
	global_load_lds_dwordx4 v[220:221], off
	v_lshl_add_u64 v[220:221], s[60:61], 0, v[152:153]
	s_mov_b32 m0, s54
	s_nop 0
	global_load_lds_dwordx4 v[220:221], off
	s_mov_b32 m0, s55
	s_nop 0
	global_load_lds_dwordx4 v[222:223], off
	s_waitcnt vmcnt(8)
	s_waitcnt lgkmcnt(0)
	s_barrier
	s_setprio 1
	s_waitcnt lgkmcnt(0)
	v_mfma_f32_16x16x32_bf16 v[60:63], v[128:131], v[176:179], v[60:63]
	v_mfma_f32_16x16x32_bf16 v[56:59], v[136:139], v[176:179], v[56:59]
	v_mfma_f32_16x16x32_bf16 v[44:47], v[128:131], v[192:195], v[44:47]
	v_mfma_f32_16x16x32_bf16 v[40:43], v[136:139], v[192:195], v[40:43]
	v_mfma_f32_16x16x32_bf16 v[28:31], v[128:131], v[200:203], v[28:31]
	v_mfma_f32_16x16x32_bf16 v[24:27], v[136:139], v[200:203], v[24:27]
	v_mfma_f32_16x16x32_bf16 v[12:15], v[128:131], v[208:211], v[12:15]
	v_mfma_f32_16x16x32_bf16 v[8:11], v[136:139], v[208:211], v[8:11]
	v_mfma_f32_16x16x32_bf16 v[60:63], v[132:135], v[180:183], v[60:63]
	v_mfma_f32_16x16x32_bf16 v[56:59], v[140:143], v[180:183], v[56:59]
	v_mfma_f32_16x16x32_bf16 v[44:47], v[132:135], v[196:199], v[44:47]
	v_mfma_f32_16x16x32_bf16 v[40:43], v[140:143], v[196:199], v[40:43]
	v_mfma_f32_16x16x32_bf16 v[28:31], v[132:135], v[204:207], v[28:31]
	v_mfma_f32_16x16x32_bf16 v[24:27], v[140:143], v[204:207], v[24:27]
	v_mfma_f32_16x16x32_bf16 v[12:15], v[132:135], v[212:215], v[12:15]
	v_mfma_f32_16x16x32_bf16 v[8:11], v[140:143], v[212:215], v[8:11]
	s_setprio 0
	s_setprio 1
	v_mfma_f32_16x16x32_bf16 v[52:55], v[144:147], v[176:179], v[52:55]
	v_mfma_f32_16x16x32_bf16 v[48:51], v[168:171], v[176:179], v[48:51]
	v_mfma_f32_16x16x32_bf16 v[36:39], v[144:147], v[192:195], v[36:39]
	v_mfma_f32_16x16x32_bf16 v[32:35], v[168:171], v[192:195], v[32:35]
	v_mfma_f32_16x16x32_bf16 v[20:23], v[144:147], v[200:203], v[20:23]
	v_mfma_f32_16x16x32_bf16 v[16:19], v[168:171], v[200:203], v[16:19]
	v_mfma_f32_16x16x32_bf16 v[4:7], v[144:147], v[208:211], v[4:7]
	v_mfma_f32_16x16x32_bf16 v[0:3], v[168:171], v[208:211], v[0:3]
	v_mfma_f32_16x16x32_bf16 v[52:55], v[148:151], v[180:183], v[52:55]
	v_mfma_f32_16x16x32_bf16 v[48:51], v[172:175], v[180:183], v[48:51]
	v_mfma_f32_16x16x32_bf16 v[36:39], v[148:151], v[196:199], v[36:39]
	v_mfma_f32_16x16x32_bf16 v[32:35], v[172:175], v[196:199], v[32:35]
	v_mfma_f32_16x16x32_bf16 v[20:23], v[148:151], v[204:207], v[20:23]
	v_mfma_f32_16x16x32_bf16 v[16:19], v[172:175], v[204:207], v[16:19]
	v_mfma_f32_16x16x32_bf16 v[4:7], v[148:151], v[212:215], v[4:7]
	v_mfma_f32_16x16x32_bf16 v[0:3], v[172:175], v[212:215], v[0:3]
	s_setprio 0
	s_barrier
	s_add_i32 s78, 0, 0x18000
	s_add_i32 s79, 0, 0x1c000
	v_add_u32_e32 v140, s78, v185
	v_add_u32_e32 v172, s79, v185
	ds_read_b128 v[128:131], v140
	ds_read_b128 v[132:135], v140 offset:1024
	ds_read_b128 v[136:139], v140 offset:2048
	ds_read_b128 v[140:143], v140 offset:3072
	ds_read_b128 v[144:147], v172
	ds_read_b128 v[148:151], v172 offset:1024
	ds_read_b128 v[168:171], v172 offset:2048
	ds_read_b128 v[172:175], v172 offset:3072
	s_add_u32 s36, s60, 0xb0000
	s_addc_u32 s37, s61, 0
	s_mov_b32 m0, s56
	v_lshl_add_u64 v[224:225], s[36:37], 0, v[152:153]
	ds_read_b128 v[176:179], v189 offset:32768
	ds_read_b128 v[180:183], v189 offset:33792
	ds_read_b128 v[192:195], v189 offset:34816
	ds_read_b128 v[196:199], v189 offset:35840
	ds_read_b128 v[200:203], v189 offset:36864
	ds_read_b128 v[204:207], v189 offset:37888
	ds_read_b128 v[208:211], v189 offset:38912
	ds_read_b128 v[212:215], v189 offset:39936
	global_load_lds_dwordx4 v[224:225], off
	v_lshl_add_u64 v[224:225], s[36:37], 0, v[156:157]
	s_mov_b32 m0, s57
	s_nop 0
	global_load_lds_dwordx4 v[224:225], off
	s_waitcnt vmcnt(8)
	s_waitcnt lgkmcnt(0)
	s_barrier
	s_setprio 1
	s_waitcnt lgkmcnt(0)
	v_mfma_f32_16x16x32_bf16 v[124:127], v[128:131], v[176:179], v[124:127]
	v_mfma_f32_16x16x32_bf16 v[120:123], v[136:139], v[176:179], v[120:123]
	v_mfma_f32_16x16x32_bf16 v[108:111], v[128:131], v[192:195], v[108:111]
	v_mfma_f32_16x16x32_bf16 v[104:107], v[136:139], v[192:195], v[104:107]
	v_mfma_f32_16x16x32_bf16 v[92:95], v[128:131], v[200:203], v[92:95]
	v_mfma_f32_16x16x32_bf16 v[88:91], v[136:139], v[200:203], v[88:91]
	v_mfma_f32_16x16x32_bf16 v[76:79], v[128:131], v[208:211], v[76:79]
	v_mfma_f32_16x16x32_bf16 v[72:75], v[136:139], v[208:211], v[72:75]
	v_mfma_f32_16x16x32_bf16 v[124:127], v[132:135], v[180:183], v[124:127]
	v_mfma_f32_16x16x32_bf16 v[120:123], v[140:143], v[180:183], v[120:123]
	v_mfma_f32_16x16x32_bf16 v[108:111], v[132:135], v[196:199], v[108:111]
	v_mfma_f32_16x16x32_bf16 v[104:107], v[140:143], v[196:199], v[104:107]
	v_mfma_f32_16x16x32_bf16 v[92:95], v[132:135], v[204:207], v[92:95]
	v_mfma_f32_16x16x32_bf16 v[88:91], v[140:143], v[204:207], v[88:91]
	v_mfma_f32_16x16x32_bf16 v[76:79], v[132:135], v[212:215], v[76:79]
	v_mfma_f32_16x16x32_bf16 v[72:75], v[140:143], v[212:215], v[72:75]
	s_setprio 0
	s_setprio 1
	v_mfma_f32_16x16x32_bf16 v[116:119], v[144:147], v[176:179], v[116:119]
	v_mfma_f32_16x16x32_bf16 v[112:115], v[168:171], v[176:179], v[112:115]
	v_mfma_f32_16x16x32_bf16 v[100:103], v[144:147], v[192:195], v[100:103]
	v_mfma_f32_16x16x32_bf16 v[96:99], v[168:171], v[192:195], v[96:99]
	v_mfma_f32_16x16x32_bf16 v[84:87], v[144:147], v[200:203], v[84:87]
	v_mfma_f32_16x16x32_bf16 v[80:83], v[168:171], v[200:203], v[80:83]
	v_mfma_f32_16x16x32_bf16 v[68:71], v[144:147], v[208:211], v[68:71]
	v_mfma_f32_16x16x32_bf16 v[64:67], v[168:171], v[208:211], v[64:67]
	v_mfma_f32_16x16x32_bf16 v[116:119], v[148:151], v[180:183], v[116:119]
	v_mfma_f32_16x16x32_bf16 v[112:115], v[172:175], v[180:183], v[112:115]
	v_mfma_f32_16x16x32_bf16 v[100:103], v[148:151], v[196:199], v[100:103]
	v_mfma_f32_16x16x32_bf16 v[96:99], v[172:175], v[196:199], v[96:99]
	v_mfma_f32_16x16x32_bf16 v[84:87], v[148:151], v[204:207], v[84:87]
	v_mfma_f32_16x16x32_bf16 v[80:83], v[172:175], v[204:207], v[80:83]
	v_mfma_f32_16x16x32_bf16 v[68:71], v[148:151], v[212:215], v[68:71]
	v_mfma_f32_16x16x32_bf16 v[64:67], v[172:175], v[212:215], v[64:67]
	s_setprio 0
	s_barrier
	s_add_i32 s36, s78, s53
	v_lshl_add_u64 v[216:217], v[216:217], 0, s[14:15]
	s_mov_b32 m0, s36
	ds_read_b128 v[176:179], v189 offset:49152
	ds_read_b128 v[180:183], v189 offset:50176
	ds_read_b128 v[192:195], v189 offset:51200
	ds_read_b128 v[196:199], v189 offset:52224
	ds_read_b128 v[200:203], v189 offset:53248
	ds_read_b128 v[204:207], v189 offset:54272
	ds_read_b128 v[208:211], v189 offset:55296
	ds_read_b128 v[212:215], v189 offset:56320
	global_load_lds_dwordx4 v[216:217], off
	s_add_i32 m0, s36, 0x2000
	s_add_u32 s36, s44, 0xb0080
	v_lshl_add_u64 v[216:217], v[218:219], 0, s[14:15]
	s_addc_u32 s37, s45, 0
	s_add_i32 s44, s79, s53
	global_load_lds_dwordx4 v[216:217], off
	v_lshl_add_u64 v[216:217], s[36:37], 0, v[154:155]
	s_mov_b32 m0, s44
	s_nop 0
	global_load_lds_dwordx4 v[216:217], off
	v_lshl_add_u64 v[216:217], s[36:37], 0, v[158:159]
	s_add_i32 m0, s44, 0x2000
	s_nop 0
	global_load_lds_dwordx4 v[216:217], off
	v_lshl_add_u64 v[216:217], v[220:221], 0, s[14:15]
	s_mov_b32 m0, s59
	s_nop 0
	global_load_lds_dwordx4 v[216:217], off
	v_lshl_add_u64 v[216:217], v[222:223], 0, s[14:15]
	s_mov_b32 m0, s62
	s_nop 0
	global_load_lds_dwordx4 v[216:217], off
	s_waitcnt vmcnt(8)
	s_waitcnt lgkmcnt(0)
	s_barrier
	s_setprio 1
	s_waitcnt lgkmcnt(0)
	v_mfma_f32_16x16x32_bf16 v[60:63], v[128:131], v[176:179], v[60:63]
	v_mfma_f32_16x16x32_bf16 v[56:59], v[136:139], v[176:179], v[56:59]
	v_mfma_f32_16x16x32_bf16 v[44:47], v[128:131], v[192:195], v[44:47]
	v_mfma_f32_16x16x32_bf16 v[40:43], v[136:139], v[192:195], v[40:43]
	v_mfma_f32_16x16x32_bf16 v[28:31], v[128:131], v[200:203], v[28:31]
	v_mfma_f32_16x16x32_bf16 v[24:27], v[136:139], v[200:203], v[24:27]
	v_mfma_f32_16x16x32_bf16 v[12:15], v[128:131], v[208:211], v[12:15]
	v_mfma_f32_16x16x32_bf16 v[8:11], v[136:139], v[208:211], v[8:11]
	v_mfma_f32_16x16x32_bf16 v[60:63], v[132:135], v[180:183], v[60:63]
	v_mfma_f32_16x16x32_bf16 v[56:59], v[140:143], v[180:183], v[56:59]
	v_mfma_f32_16x16x32_bf16 v[44:47], v[132:135], v[196:199], v[44:47]
	v_mfma_f32_16x16x32_bf16 v[40:43], v[140:143], v[196:199], v[40:43]
	v_mfma_f32_16x16x32_bf16 v[28:31], v[132:135], v[204:207], v[28:31]
	v_mfma_f32_16x16x32_bf16 v[24:27], v[140:143], v[204:207], v[24:27]
	v_mfma_f32_16x16x32_bf16 v[12:15], v[132:135], v[212:215], v[12:15]
	v_mfma_f32_16x16x32_bf16 v[8:11], v[140:143], v[212:215], v[8:11]
	s_setprio 0
	s_setprio 1
	v_mfma_f32_16x16x32_bf16 v[52:55], v[144:147], v[176:179], v[52:55]
	v_mfma_f32_16x16x32_bf16 v[48:51], v[168:171], v[176:179], v[48:51]
	v_mfma_f32_16x16x32_bf16 v[36:39], v[144:147], v[192:195], v[36:39]
	v_mfma_f32_16x16x32_bf16 v[32:35], v[168:171], v[192:195], v[32:35]
	v_mfma_f32_16x16x32_bf16 v[20:23], v[144:147], v[200:203], v[20:23]
	v_mfma_f32_16x16x32_bf16 v[16:19], v[168:171], v[200:203], v[16:19]
	v_mfma_f32_16x16x32_bf16 v[4:7], v[144:147], v[208:211], v[4:7]
	v_mfma_f32_16x16x32_bf16 v[0:3], v[168:171], v[208:211], v[0:3]
	v_mfma_f32_16x16x32_bf16 v[52:55], v[148:151], v[180:183], v[52:55]
	v_mfma_f32_16x16x32_bf16 v[48:51], v[172:175], v[180:183], v[48:51]
	v_mfma_f32_16x16x32_bf16 v[36:39], v[148:151], v[196:199], v[36:39]
	v_mfma_f32_16x16x32_bf16 v[32:35], v[172:175], v[196:199], v[32:35]
	v_mfma_f32_16x16x32_bf16 v[20:23], v[148:151], v[204:207], v[20:23]
	v_mfma_f32_16x16x32_bf16 v[16:19], v[172:175], v[204:207], v[16:19]
	v_mfma_f32_16x16x32_bf16 v[4:7], v[148:151], v[212:215], v[4:7]
	v_mfma_f32_16x16x32_bf16 v[0:3], v[172:175], v[212:215], v[0:3]
	s_setprio 0
	s_barrier
	s_add_i32 s77, s77, 2
	s_add_u32 s73, s73, 0x100
	s_addc_u32 s76, s76, 0
	s_cmp_gt_u32 s77, 41
	s_mov_b64 s[36:37], s[38:39]
	s_cbranch_scc0 .LBB0_1080
	v_lshl_add_u32 v168, s72, 8, v184
	v_lshl_or_b32 v128, s18, 8, v186
	v_ashrrev_i32_e32 v169, 31, v168
	v_ashrrev_i32_e32 v129, 31, v128
	v_lshlrev_b64 v[130:131], 11, v[168:169]
	v_lshl_add_u64 v[130:131], s[34:35], 0, v[130:131]
	v_lshlrev_b64 v[170:171], 1, v[128:129]
	v_lshl_add_u64 v[200:201], v[130:131], 0, v[170:171]
	global_load_dwordx4 v[192:195], v[200:201], off
	global_load_dwordx4 v[196:199], v[200:201], off offset:256
	v_or_b32_e32 v180, 16, v168
	v_or_b32_e32 v176, 32, v168
	v_or_b32_e32 v172, 48, v168
	v_ashrrev_i32_e32 v181, 31, v180
	v_ashrrev_i32_e32 v177, 31, v176
	v_ashrrev_i32_e32 v173, 31, v172
	v_lshlrev_b64 v[128:129], 11, v[180:181]
	v_lshlrev_b64 v[130:131], 11, v[176:177]
	v_lshlrev_b64 v[132:133], 11, v[172:173]
	v_lshl_add_u64 v[128:129], s[34:35], 0, v[128:129]
	v_lshl_add_u64 v[130:131], s[34:35], 0, v[130:131]
	v_lshl_add_u64 v[132:133], s[34:35], 0, v[132:133]
	v_lshl_add_u64 v[182:183], v[128:129], 0, v[170:171]
	v_lshl_add_u64 v[178:179], v[130:131], 0, v[170:171]
	v_lshl_add_u64 v[174:175], v[132:133], 0, v[170:171]
	global_load_dwordx4 v[148:151], v[182:183], off
	global_load_dwordx4 v[144:147], v[182:183], off offset:256
	global_load_dwordx4 v[140:143], v[178:179], off
	global_load_dwordx4 v[136:139], v[178:179], off offset:256
	global_load_dwordx4 v[132:135], v[174:175], off
	global_load_dwordx4 v[128:131], v[174:175], off offset:256
	v_add_u32_e32 v224, 0x80, v168
	v_ashrrev_i32_e32 v225, 31, v224
	v_lshlrev_b64 v[224:225], 11, v[224:225]
	v_lshl_add_u64 v[224:225], s[34:35], 0, v[224:225]
	v_lshl_add_u64 v[212:213], v[224:225], 0, v[170:171]
	global_load_dwordx4 v[226:229], v[212:213], off
	global_load_dwordx4 v[230:233], v[212:213], off offset:256
	v_add_u32_e32 v224, 0x90, v168
	v_ashrrev_i32_e32 v225, 31, v224
	v_lshlrev_b64 v[224:225], 11, v[224:225]
	v_lshl_add_u64 v[224:225], s[34:35], 0, v[224:225]
	v_lshl_add_u64 v[214:215], v[224:225], 0, v[170:171]
	global_load_dwordx4 v[234:237], v[214:215], off
	global_load_dwordx4 v[238:241], v[214:215], off offset:256
	v_add_u32_e32 v224, 0xa0, v168
	v_ashrrev_i32_e32 v225, 31, v224
	v_lshlrev_b64 v[224:225], 11, v[224:225]
	v_lshl_add_u64 v[224:225], s[34:35], 0, v[224:225]
	v_lshl_add_u64 v[216:217], v[224:225], 0, v[170:171]
	global_load_dwordx4 v[242:245], v[216:217], off
	global_load_dwordx4 v[246:249], v[216:217], off offset:256
	v_add_u32_e32 v224, 0xb0, v168
	v_ashrrev_i32_e32 v225, 31, v224
	v_lshlrev_b64 v[224:225], 11, v[224:225]
	v_lshl_add_u64 v[224:225], s[34:35], 0, v[224:225]
	v_lshl_add_u64 v[218:219], v[224:225], 0, v[170:171]
	global_load_dwordx4 v[250:253], v[218:219], off
	global_load_dwordx4 v[220:223], v[218:219], off offset:256
	v_and_b32_e32 v202, 64, v190
	v_xor_b32_e32 v191, 16, v190
	v_add_u32_e32 v202, 64, v202
	v_xor_b32_e32 v203, 32, v190
	v_cmp_lt_i32_e32 vcc, v191, v202
	s_lshl_b32 s36, s18, 2
	s_ashr_i32 s37, s36, 31
	v_cndmask_b32_e32 v191, v190, v191, vcc
	v_cmp_lt_i32_e32 vcc, v203, v202
	v_lshlrev_b32_e32 v191, 2, v191
	s_waitcnt vmcnt(8)
	v_lshlrev_b32_e32 v202, 16, v192
	v_cndmask_b32_e32 v210, v190, v203, vcc
	v_and_b32_e32 v203, 0xffff0000, v192
	v_lshlrev_b32_e32 v192, 16, v193
	v_and_b32_e32 v193, 0xffff0000, v193
	v_lshlrev_b32_e32 v204, 16, v194
	v_and_b32_e32 v205, 0xffff0000, v194
	v_lshlrev_b32_e32 v194, 16, v195
	v_and_b32_e32 v195, 0xffff0000, v195
	v_lshlrev_b32_e32 v206, 16, v196
	v_and_b32_e32 v207, 0xffff0000, v196
	v_lshlrev_b32_e32 v196, 16, v197
	v_and_b32_e32 v197, 0xffff0000, v197
	v_lshlrev_b32_e32 v208, 16, v198
	v_and_b32_e32 v209, 0xffff0000, v198
	v_lshlrev_b32_e32 v198, 16, v199
	v_and_b32_e32 v199, 0xffff0000, v199
	v_pk_add_f32 v[126:127], v[126:127], v[192:193]
	v_pk_add_f32 v[124:125], v[124:125], v[202:203]
	v_pk_add_f32 v[122:123], v[122:123], v[194:195]
	v_pk_add_f32 v[120:121], v[120:121], v[204:205]
	v_pk_add_f32 v[118:119], v[118:119], v[196:197]
	v_pk_add_f32 v[116:117], v[116:117], v[206:207]
	v_pk_add_f32 v[192:193], v[114:115], v[198:199]
	v_pk_add_f32 v[194:195], v[112:113], v[208:209]
	v_cvt_pk_bf16_f32 v112, v124, v125
	v_cvt_pk_bf16_f32 v113, v126, v127
	v_mul_f32_e32 v114, v125, v125
	v_mul_f32_e32 v115, v127, v127
	v_mul_f32_e32 v125, v121, v121
	v_mul_f32_e32 v127, v123, v123
	v_mul_f32_e32 v196, v117, v117
	v_mul_f32_e32 v197, v119, v119
	v_mul_f32_e32 v198, v195, v195
	v_mul_f32_e32 v199, v193, v193
	v_fmac_f32_e32 v114, v124, v124
	v_fmac_f32_e32 v115, v126, v126
	v_fmac_f32_e32 v125, v120, v120
	v_fmac_f32_e32 v127, v122, v122
	v_fmac_f32_e32 v196, v116, v116
	v_fmac_f32_e32 v197, v118, v118
	v_fmac_f32_e32 v198, v194, v194
	v_fmac_f32_e32 v199, v192, v192
	v_add_f32_e32 v114, v114, v115
	v_add_f32_e32 v115, v125, v127
	v_add_f32_e32 v124, v196, v197
	v_add_f32_e32 v125, v198, v199
	v_add_f32_e32 v114, v114, v115
	v_add_f32_e32 v115, v124, v125
	v_add_f32_e32 v124, v114, v115
	ds_bpermute_b32 v125, v191, v124
	v_cvt_pk_bf16_f32 v114, v120, v121
	v_cvt_pk_bf16_f32 v115, v122, v123
	global_store_dwordx4 v[200:201], v[112:115], off
	v_cvt_pk_bf16_f32 v116, v116, v117
	v_cvt_pk_bf16_f32 v117, v118, v119
	s_waitcnt lgkmcnt(0)
	v_add_f32_e32 v113, v124, v125
	v_lshlrev_b32_e32 v112, 2, v210
	ds_bpermute_b32 v114, v112, v113
	v_cvt_pk_bf16_f32 v118, v194, v195
	v_cvt_pk_bf16_f32 v119, v192, v193
	global_store_dwordx4 v[200:201], v[116:119], off offset:256
	s_and_saveexec_b64 s[38:39], s[0:1]
	s_cbranch_execz .LBB0_1083
	s_waitcnt lgkmcnt(0)
	v_add_f32_e32 v113, v113, v114
	v_lshlrev_b64 v[114:115], 6, v[168:169]
	v_lshl_add_u64 v[114:115], s[74:75], 0, v[114:115]
	v_lshl_add_u64 v[114:115], s[36:37], 2, v[114:115]
	s_lshl_b32 s18, s58, 2
	v_lshl_add_u64 v[114:115], v[114:115], 0, s[18:19]
	global_store_dword v[114:115], v113, off

.LBB0_1089:
	s_or_b64 exec, exec, s[38:39]
	v_add_u32_e32 v100, 0x80, v168
	v_ashrrev_i32_e32 v101, 31, v100
	s_waitcnt lgkmcnt(0)
	v_lshlrev_b64 v[64:65], 11, v[100:101]
	v_lshl_add_u64 v[64:65], s[34:35], 0, v[64:65]
	v_lshl_add_u64 v[110:111], v[64:65], 0, v[170:171]
	s_waitcnt vmcnt(8)
	v_mov_b64_e32 v[102:103], v[226:227]
	v_mov_b64_e32 v[104:105], v[228:229]
	v_mov_b64_e32 v[106:107], v[230:231]
	v_mov_b64_e32 v[108:109], v[232:233]
	v_add_u32_e32 v96, 0x90, v168
	v_add_u32_e32 v92, 0xa0, v168
	v_add_u32_e32 v88, 0xb0, v168
	v_ashrrev_i32_e32 v97, 31, v96
	v_ashrrev_i32_e32 v93, 31, v92
	v_ashrrev_i32_e32 v89, 31, v88
	v_lshlrev_b64 v[64:65], 11, v[96:97]
	v_lshlrev_b64 v[66:67], 11, v[92:93]
	v_lshlrev_b64 v[68:69], 11, v[88:89]
	v_lshl_add_u64 v[64:65], s[34:35], 0, v[64:65]
	v_lshl_add_u64 v[66:67], s[34:35], 0, v[66:67]
	v_lshl_add_u64 v[68:69], s[34:35], 0, v[68:69]
	v_lshl_add_u64 v[98:99], v[64:65], 0, v[170:171]
	v_lshl_add_u64 v[94:95], v[66:67], 0, v[170:171]
	v_lshl_add_u64 v[90:91], v[68:69], 0, v[170:171]
	v_mov_b64_e32 v[84:85], v[234:235]
	v_mov_b64_e32 v[86:87], v[236:237]
	v_mov_b64_e32 v[80:81], v[238:239]
	v_mov_b64_e32 v[82:83], v[240:241]
	v_mov_b64_e32 v[76:77], v[242:243]
	v_mov_b64_e32 v[78:79], v[244:245]
	v_mov_b64_e32 v[72:73], v[246:247]
	v_mov_b64_e32 v[74:75], v[248:249]
	v_mov_b64_e32 v[68:69], v[250:251]
	v_mov_b64_e32 v[70:71], v[252:253]
	v_mov_b64_e32 v[64:65], v[220:221]
	v_mov_b64_e32 v[66:67], v[222:223]
	s_nop 0
	v_lshlrev_b32_e32 v114, 16, v102
	v_and_b32_e32 v115, 0xffff0000, v102
	v_lshlrev_b32_e32 v102, 16, v103
	v_and_b32_e32 v103, 0xffff0000, v103
	v_lshlrev_b32_e32 v116, 16, v104
	v_and_b32_e32 v117, 0xffff0000, v104
	v_lshlrev_b32_e32 v104, 16, v105
	v_and_b32_e32 v105, 0xffff0000, v105
	s_nop 0
	v_lshlrev_b32_e32 v118, 16, v106
	v_and_b32_e32 v119, 0xffff0000, v106
	v_lshlrev_b32_e32 v106, 16, v107
	v_and_b32_e32 v107, 0xffff0000, v107
	v_lshlrev_b32_e32 v120, 16, v108
	v_and_b32_e32 v121, 0xffff0000, v108
	v_lshlrev_b32_e32 v108, 16, v109
	v_and_b32_e32 v109, 0xffff0000, v109
	v_pk_add_f32 v[62:63], v[62:63], v[102:103]
	v_pk_add_f32 v[60:61], v[60:61], v[114:115]
	v_pk_add_f32 v[58:59], v[58:59], v[104:105]
	v_pk_add_f32 v[56:57], v[56:57], v[116:117]
	v_pk_add_f32 v[54:55], v[54:55], v[106:107]
	v_pk_add_f32 v[52:53], v[52:53], v[118:119]
	v_pk_add_f32 v[102:103], v[50:51], v[108:109]
	v_pk_add_f32 v[104:105], v[48:49], v[120:121]
	v_cvt_pk_bf16_f32 v48, v60, v61
	v_cvt_pk_bf16_f32 v49, v62, v63
	v_mul_f32_e32 v50, v61, v61
	v_mul_f32_e32 v51, v63, v63
	v_mul_f32_e32 v61, v57, v57
	v_mul_f32_e32 v63, v59, v59
	v_mul_f32_e32 v106, v53, v53
	v_mul_f32_e32 v107, v55, v55
	v_mul_f32_e32 v108, v105, v105
	v_mul_f32_e32 v109, v103, v103
	v_fmac_f32_e32 v50, v60, v60
	v_fmac_f32_e32 v51, v62, v62
	v_fmac_f32_e32 v61, v56, v56
	v_fmac_f32_e32 v63, v58, v58
	v_fmac_f32_e32 v106, v52, v52
	v_fmac_f32_e32 v107, v54, v54
	v_fmac_f32_e32 v108, v104, v104
	v_fmac_f32_e32 v109, v102, v102
	v_add_f32_e32 v50, v50, v51
	v_add_f32_e32 v51, v61, v63
	v_add_f32_e32 v60, v106, v107
	v_add_f32_e32 v61, v108, v109
	v_add_f32_e32 v50, v50, v51
	v_add_f32_e32 v51, v60, v61
	v_add_f32_e32 v60, v50, v51
	ds_bpermute_b32 v61, v191, v60
	v_cvt_pk_bf16_f32 v50, v56, v57
	v_cvt_pk_bf16_f32 v51, v58, v59
	global_store_dwordx4 v[110:111], v[48:51], off
	s_waitcnt lgkmcnt(0)
	s_nop 0
	v_add_f32_e32 v48, v60, v61
	ds_bpermute_b32 v49, v112, v48
	v_cvt_pk_bf16_f32 v50, v52, v53
	v_cvt_pk_bf16_f32 v51, v54, v55
	v_cvt_pk_bf16_f32 v52, v104, v105
	v_cvt_pk_bf16_f32 v53, v102, v103
	global_store_dwordx4 v[110:111], v[50:53], off offset:256
	s_and_saveexec_b64 s[38:39], s[0:1]
	s_cbranch_execz .LBB0_1091
	s_waitcnt lgkmcnt(0)
	v_add_f32_e32 v50, v48, v49
	v_lshlrev_b64 v[48:49], 6, v[100:101]
	v_lshl_add_u64 v[48:49], s[74:75], 0, v[48:49]
	v_lshl_add_u64 v[48:49], s[36:37], 2, v[48:49]
	s_lshl_b32 s18, s58, 2
	v_lshl_add_u64 v[48:49], v[48:49], 0, s[18:19]
	global_store_dword v[48:49], v50, off
.LBB0_1091:
	s_or_b64 exec, exec, s[38:39]
	s_nop 0
	v_lshlrev_b32_e32 v48, 16, v84
	s_waitcnt lgkmcnt(0)
	v_and_b32_e32 v49, 0xffff0000, v84
	v_lshlrev_b32_e32 v50, 16, v85
	v_and_b32_e32 v51, 0xffff0000, v85
	v_lshlrev_b32_e32 v52, 16, v86
	v_and_b32_e32 v53, 0xffff0000, v86
	v_lshlrev_b32_e32 v54, 16, v87
	v_and_b32_e32 v55, 0xffff0000, v87
	s_nop 0
	v_lshlrev_b32_e32 v60, 16, v82
	v_and_b32_e32 v61, 0xffff0000, v82
	v_pk_add_f32 v[46:47], v[46:47], v[50:51]
	v_pk_add_f32 v[44:45], v[44:45], v[48:49]
	v_pk_add_f32 v[48:49], v[42:43], v[54:55]
	v_pk_add_f32 v[42:43], v[40:41], v[52:53]
	v_pk_add_f32 v[52:53], v[32:33], v[60:61]
	v_mul_f32_e32 v32, v45, v45
	v_mul_f32_e32 v33, v47, v47
	v_lshlrev_b32_e32 v62, 16, v83
	v_and_b32_e32 v63, 0xffff0000, v83
	v_fmac_f32_e32 v32, v44, v44
	v_fmac_f32_e32 v33, v46, v46
	v_pk_add_f32 v[50:51], v[34:35], v[62:63]
	v_add_f32_e32 v32, v32, v33
	v_mul_f32_e32 v33, v43, v43
	v_mul_f32_e32 v34, v49, v49
	v_lshlrev_b32_e32 v56, 16, v80
	v_and_b32_e32 v57, 0xffff0000, v80
	v_lshlrev_b32_e32 v58, 16, v81
	v_and_b32_e32 v59, 0xffff0000, v81
	v_fmac_f32_e32 v33, v42, v42
	v_fmac_f32_e32 v34, v48, v48
	v_pk_add_f32 v[38:39], v[38:39], v[58:59]
	v_pk_add_f32 v[36:37], v[36:37], v[56:57]
	v_add_f32_e32 v33, v33, v34
	v_add_f32_e32 v32, v32, v33
	v_mul_f32_e32 v33, v37, v37
	v_mul_f32_e32 v34, v39, v39
	v_fmac_f32_e32 v33, v36, v36
	v_fmac_f32_e32 v34, v38, v38
	v_add_f32_e32 v33, v33, v34
	v_mul_f32_e32 v34, v53, v53
	v_mul_f32_e32 v35, v51, v51
	v_fmac_f32_e32 v34, v52, v52
	v_fmac_f32_e32 v35, v50, v50
	v_add_f32_e32 v34, v34, v35
	v_add_f32_e32 v33, v33, v34
	v_add_f32_e32 v32, v32, v33
	ds_bpermute_b32 v33, v191, v32
	v_cvt_pk_bf16_f32 v40, v44, v45
	v_cvt_pk_bf16_f32 v41, v46, v47
	v_cvt_pk_bf16_f32 v42, v42, v43
	v_cvt_pk_bf16_f32 v43, v48, v49
	s_waitcnt lgkmcnt(0)
	v_add_f32_e32 v32, v32, v33
	ds_bpermute_b32 v33, v112, v32
	v_cvt_pk_bf16_f32 v34, v36, v37
	v_cvt_pk_bf16_f32 v35, v38, v39
	v_cvt_pk_bf16_f32 v36, v52, v53
	v_cvt_pk_bf16_f32 v37, v50, v51
	global_store_dwordx4 v[98:99], v[40:43], off
	global_store_dwordx4 v[98:99], v[34:37], off offset:256
	s_and_saveexec_b64 s[38:39], s[0:1]
	s_cbranch_execz .LBB0_1093
	s_waitcnt lgkmcnt(0)
	v_add_f32_e32 v34, v32, v33
	v_lshlrev_b64 v[32:33], 6, v[96:97]
	v_lshl_add_u64 v[32:33], s[74:75], 0, v[32:33]
	v_lshl_add_u64 v[32:33], s[36:37], 2, v[32:33]
	s_lshl_b32 s18, s58, 2
	v_lshl_add_u64 v[32:33], v[32:33], 0, s[18:19]
	global_store_dword v[32:33], v34, off
.LBB0_1093:
	s_or_b64 exec, exec, s[38:39]
	s_nop 0
	v_lshlrev_b32_e32 v32, 16, v76
	s_waitcnt lgkmcnt(0)
	v_and_b32_e32 v33, 0xffff0000, v76
	v_lshlrev_b32_e32 v34, 16, v77
	v_and_b32_e32 v35, 0xffff0000, v77
	v_lshlrev_b32_e32 v36, 16, v78
	v_and_b32_e32 v37, 0xffff0000, v78
	v_lshlrev_b32_e32 v38, 16, v79
	v_and_b32_e32 v39, 0xffff0000, v79
	s_nop 0
	v_lshlrev_b32_e32 v44, 16, v74
	v_and_b32_e32 v45, 0xffff0000, v74
	v_pk_add_f32 v[30:31], v[30:31], v[34:35]
	v_pk_add_f32 v[28:29], v[28:29], v[32:33]
	v_pk_add_f32 v[32:33], v[26:27], v[38:39]
	v_pk_add_f32 v[26:27], v[24:25], v[36:37]
	v_pk_add_f32 v[36:37], v[16:17], v[44:45]
	v_mul_f32_e32 v16, v29, v29
	v_mul_f32_e32 v17, v31, v31
	v_lshlrev_b32_e32 v46, 16, v75
	v_and_b32_e32 v47, 0xffff0000, v75
	v_fmac_f32_e32 v16, v28, v28
	v_fmac_f32_e32 v17, v30, v30
	v_pk_add_f32 v[34:35], v[18:19], v[46:47]
	v_add_f32_e32 v16, v16, v17
	v_mul_f32_e32 v17, v27, v27
	v_mul_f32_e32 v18, v33, v33
	v_lshlrev_b32_e32 v40, 16, v72
	v_and_b32_e32 v41, 0xffff0000, v72
	v_lshlrev_b32_e32 v42, 16, v73
	v_and_b32_e32 v43, 0xffff0000, v73
	v_fmac_f32_e32 v17, v26, v26
	v_fmac_f32_e32 v18, v32, v32
	v_pk_add_f32 v[22:23], v[22:23], v[42:43]
	v_pk_add_f32 v[20:21], v[20:21], v[40:41]
	v_add_f32_e32 v17, v17, v18
	v_add_f32_e32 v16, v16, v17
	v_mul_f32_e32 v17, v21, v21
	v_mul_f32_e32 v18, v23, v23
	v_fmac_f32_e32 v17, v20, v20
	v_fmac_f32_e32 v18, v22, v22
	v_add_f32_e32 v17, v17, v18
	v_mul_f32_e32 v18, v37, v37
	v_mul_f32_e32 v19, v35, v35
	v_fmac_f32_e32 v18, v36, v36
	v_fmac_f32_e32 v19, v34, v34
	v_add_f32_e32 v18, v18, v19
	v_add_f32_e32 v17, v17, v18
	v_add_f32_e32 v16, v16, v17
	ds_bpermute_b32 v17, v191, v16
	v_cvt_pk_bf16_f32 v24, v28, v29
	v_cvt_pk_bf16_f32 v25, v30, v31
	v_cvt_pk_bf16_f32 v26, v26, v27
	v_cvt_pk_bf16_f32 v27, v32, v33
	s_waitcnt lgkmcnt(0)
	v_add_f32_e32 v16, v16, v17
	ds_bpermute_b32 v17, v112, v16
	v_cvt_pk_bf16_f32 v18, v20, v21
	v_cvt_pk_bf16_f32 v19, v22, v23
	v_cvt_pk_bf16_f32 v20, v36, v37
	v_cvt_pk_bf16_f32 v21, v34, v35
	global_store_dwordx4 v[94:95], v[24:27], off
	global_store_dwordx4 v[94:95], v[18:21], off offset:256
	s_and_saveexec_b64 s[38:39], s[0:1]
	s_cbranch_execz .LBB0_1095
	s_waitcnt lgkmcnt(0)
	v_add_f32_e32 v18, v16, v17
	v_lshlrev_b64 v[16:17], 6, v[92:93]
	v_lshl_add_u64 v[16:17], s[74:75], 0, v[16:17]
	v_lshl_add_u64 v[16:17], s[36:37], 2, v[16:17]
	s_lshl_b32 s18, s58, 2
	v_lshl_add_u64 v[16:17], v[16:17], 0, s[18:19]
	global_store_dword v[16:17], v18, off
.LBB0_1095:
	s_or_b64 exec, exec, s[38:39]
	s_nop 0
	v_lshlrev_b32_e32 v16, 16, v68
	s_waitcnt lgkmcnt(0)
	v_and_b32_e32 v17, 0xffff0000, v68
	v_lshlrev_b32_e32 v18, 16, v69
	v_and_b32_e32 v19, 0xffff0000, v69
	v_lshlrev_b32_e32 v20, 16, v70
	v_and_b32_e32 v21, 0xffff0000, v70
	v_lshlrev_b32_e32 v22, 16, v71
	v_and_b32_e32 v23, 0xffff0000, v71
	s_nop 0
	v_lshlrev_b32_e32 v28, 16, v66
	v_and_b32_e32 v29, 0xffff0000, v66
	v_pk_add_f32 v[14:15], v[14:15], v[18:19]
	v_pk_add_f32 v[12:13], v[12:13], v[16:17]
	v_pk_add_f32 v[16:17], v[10:11], v[22:23]
	v_pk_add_f32 v[10:11], v[8:9], v[20:21]
	v_pk_add_f32 v[20:21], v[0:1], v[28:29]
	v_mul_f32_e32 v0, v13, v13
	v_mul_f32_e32 v1, v15, v15
	v_lshlrev_b32_e32 v30, 16, v67
	v_and_b32_e32 v31, 0xffff0000, v67
	v_fmac_f32_e32 v0, v12, v12
	v_fmac_f32_e32 v1, v14, v14
	v_pk_add_f32 v[18:19], v[2:3], v[30:31]
	v_add_f32_e32 v0, v0, v1
	v_mul_f32_e32 v1, v11, v11
	v_mul_f32_e32 v2, v17, v17
	v_lshlrev_b32_e32 v24, 16, v64
	v_and_b32_e32 v25, 0xffff0000, v64
	v_lshlrev_b32_e32 v26, 16, v65
	v_and_b32_e32 v27, 0xffff0000, v65
	v_fmac_f32_e32 v1, v10, v10
	v_fmac_f32_e32 v2, v16, v16
	v_pk_add_f32 v[6:7], v[6:7], v[26:27]
	v_pk_add_f32 v[4:5], v[4:5], v[24:25]
	v_add_f32_e32 v1, v1, v2
	v_add_f32_e32 v0, v0, v1
	v_mul_f32_e32 v1, v5, v5
	v_mul_f32_e32 v2, v7, v7
	v_fmac_f32_e32 v1, v4, v4
	v_fmac_f32_e32 v2, v6, v6
	v_add_f32_e32 v1, v1, v2
	v_mul_f32_e32 v2, v21, v21
	v_mul_f32_e32 v3, v19, v19
	v_fmac_f32_e32 v2, v20, v20
	v_fmac_f32_e32 v3, v18, v18
	v_add_f32_e32 v2, v2, v3
	v_add_f32_e32 v1, v1, v2
	v_add_f32_e32 v0, v0, v1
	ds_bpermute_b32 v1, v191, v0
	v_cvt_pk_bf16_f32 v8, v12, v13
	v_cvt_pk_bf16_f32 v9, v14, v15
	v_cvt_pk_bf16_f32 v10, v10, v11
	v_cvt_pk_bf16_f32 v11, v16, v17
	s_waitcnt lgkmcnt(0)
	v_add_f32_e32 v0, v0, v1
	ds_bpermute_b32 v1, v112, v0
	v_cvt_pk_bf16_f32 v2, v4, v5
	v_cvt_pk_bf16_f32 v3, v6, v7
	v_cvt_pk_bf16_f32 v4, v20, v21
	v_cvt_pk_bf16_f32 v5, v18, v19
	global_store_dwordx4 v[90:91], v[8:11], off
	global_store_dwordx4 v[90:91], v[2:5], off offset:256
	s_and_saveexec_b64 s[38:39], s[0:1]
	s_cbranch_execz .LBB0_1068
	s_waitcnt lgkmcnt(0)
	v_add_f32_e32 v2, v0, v1
	v_lshlrev_b64 v[0:1], 6, v[88:89]
	v_lshl_add_u64 v[0:1], s[74:75], 0, v[0:1]
	v_lshl_add_u64 v[0:1], s[36:37], 2, v[0:1]
	s_lshl_b32 s18, s58, 2
	v_lshl_add_u64 v[0:1], v[0:1], 0, s[18:19]
	global_store_dword v[0:1], v2, off
	s_branch .LBB0_1068

.LBB0_1530:
	ds_read_b128 v[128:131], v187
	ds_read_b128 v[132:135], v187 offset:1024
	ds_read_b128 v[136:139], v187 offset:2048
	ds_read_b128 v[140:143], v187 offset:3072
	ds_read_b128 v[144:147], v188
	ds_read_b128 v[148:151], v188 offset:1024
	ds_read_b128 v[168:171], v188 offset:2048
	ds_read_b128 v[172:175], v188 offset:3072
	s_add_u32 s36, s24, 0xfffc0080
	s_addc_u32 s37, s25, -1
	s_cmp_eq_u32 s65, 12
	s_cselect_b32 s39, s11, s37
	s_cselect_b32 s38, s61, s36
	s_cselect_b32 s37, s13, s64
	s_cselect_b32 s36, s62, s63
	v_lshl_add_u64 v[216:217], s[24:25], 0, v[160:161]
	s_add_i32 m0, s46, 0xc000
	ds_read_b128 v[176:179], v189
	ds_read_b128 v[180:183], v189 offset:1024
	ds_read_b128 v[192:195], v189 offset:2048
	ds_read_b128 v[196:199], v189 offset:3072
	ds_read_b128 v[200:203], v189 offset:4096
	ds_read_b128 v[204:207], v189 offset:5120
	ds_read_b128 v[208:211], v189 offset:6144
	ds_read_b128 v[212:215], v189 offset:7168
	global_load_lds_dwordx4 v[216:217], off
	v_lshl_add_u64 v[216:217], s[24:25], 0, v[162:163]
	s_add_i32 m0, s46, 0xe000
	s_nop 0
	global_load_lds_dwordx4 v[216:217], off
	s_waitcnt vmcnt(8)
	s_waitcnt lgkmcnt(0)
	s_barrier
	s_setprio 1
	s_waitcnt lgkmcnt(0)
	v_mfma_f32_16x16x32_bf16 v[124:127], v[128:131], v[176:179], v[124:127]
	v_mfma_f32_16x16x32_bf16 v[120:123], v[136:139], v[176:179], v[120:123]
	v_mfma_f32_16x16x32_bf16 v[108:111], v[128:131], v[192:195], v[108:111]
	v_mfma_f32_16x16x32_bf16 v[104:107], v[136:139], v[192:195], v[104:107]
	v_mfma_f32_16x16x32_bf16 v[92:95], v[128:131], v[200:203], v[92:95]
	v_mfma_f32_16x16x32_bf16 v[88:91], v[136:139], v[200:203], v[88:91]
	v_mfma_f32_16x16x32_bf16 v[76:79], v[128:131], v[208:211], v[76:79]
	v_mfma_f32_16x16x32_bf16 v[72:75], v[136:139], v[208:211], v[72:75]
	v_mfma_f32_16x16x32_bf16 v[124:127], v[132:135], v[180:183], v[124:127]
	v_mfma_f32_16x16x32_bf16 v[120:123], v[140:143], v[180:183], v[120:123]
	v_mfma_f32_16x16x32_bf16 v[108:111], v[132:135], v[196:199], v[108:111]
	v_mfma_f32_16x16x32_bf16 v[104:107], v[140:143], v[196:199], v[104:107]
	v_mfma_f32_16x16x32_bf16 v[92:95], v[132:135], v[204:207], v[92:95]
	v_mfma_f32_16x16x32_bf16 v[88:91], v[140:143], v[204:207], v[88:91]
	v_mfma_f32_16x16x32_bf16 v[76:79], v[132:135], v[212:215], v[76:79]
	v_mfma_f32_16x16x32_bf16 v[72:75], v[140:143], v[212:215], v[72:75]
	s_setprio 0
	s_setprio 1
	v_mfma_f32_16x16x32_bf16 v[116:119], v[144:147], v[176:179], v[116:119]
	v_mfma_f32_16x16x32_bf16 v[112:115], v[168:171], v[176:179], v[112:115]
	v_mfma_f32_16x16x32_bf16 v[100:103], v[144:147], v[192:195], v[100:103]
	v_mfma_f32_16x16x32_bf16 v[96:99], v[168:171], v[192:195], v[96:99]
	v_mfma_f32_16x16x32_bf16 v[84:87], v[144:147], v[200:203], v[84:87]
	v_mfma_f32_16x16x32_bf16 v[80:83], v[168:171], v[200:203], v[80:83]
	v_mfma_f32_16x16x32_bf16 v[68:71], v[144:147], v[208:211], v[68:71]
	v_mfma_f32_16x16x32_bf16 v[64:67], v[168:171], v[208:211], v[64:67]
	v_mfma_f32_16x16x32_bf16 v[116:119], v[148:151], v[180:183], v[116:119]
	v_mfma_f32_16x16x32_bf16 v[112:115], v[172:175], v[180:183], v[112:115]
	v_mfma_f32_16x16x32_bf16 v[100:103], v[148:151], v[196:199], v[100:103]
	v_mfma_f32_16x16x32_bf16 v[96:99], v[172:175], v[196:199], v[96:99]
	v_mfma_f32_16x16x32_bf16 v[84:87], v[148:151], v[204:207], v[84:87]
	v_mfma_f32_16x16x32_bf16 v[80:83], v[172:175], v[204:207], v[80:83]
	v_mfma_f32_16x16x32_bf16 v[68:71], v[148:151], v[212:215], v[68:71]
	v_mfma_f32_16x16x32_bf16 v[64:67], v[172:175], v[212:215], v[64:67]
	s_setprio 0
	s_barrier
	s_add_i32 s66, s55, s45
	v_lshl_add_u64 v[216:217], s[36:37], 0, v[154:155]
	s_mov_b32 m0, s66
	ds_read_b128 v[176:179], v189 offset:16384
	ds_read_b128 v[180:183], v189 offset:17408
	ds_read_b128 v[192:195], v189 offset:18432
	ds_read_b128 v[196:199], v189 offset:19456
	ds_read_b128 v[200:203], v189 offset:20480
	ds_read_b128 v[204:207], v189 offset:21504
	ds_read_b128 v[208:211], v189 offset:22528
	ds_read_b128 v[212:215], v189 offset:23552
	global_load_lds_dwordx4 v[216:217], off
	s_add_i32 m0, s66, 0x2000
	s_add_u32 s66, s36, 0x40000
	v_lshl_add_u64 v[218:219], s[36:37], 0, v[158:159]
	s_addc_u32 s67, s37, 0
	s_add_i32 s68, s56, s45
	global_load_lds_dwordx4 v[218:219], off
	v_lshl_add_u64 v[220:221], s[66:67], 0, v[154:155]
	s_mov_b32 m0, s68
	v_lshl_add_u64 v[222:223], s[38:39], 0, v[156:157]
	global_load_lds_dwordx4 v[220:221], off
	v_lshl_add_u64 v[220:221], s[66:67], 0, v[158:159]
	s_add_i32 m0, s68, 0x2000
	s_nop 0
	global_load_lds_dwordx4 v[220:221], off
	v_lshl_add_u64 v[220:221], s[38:39], 0, v[152:153]
	s_mov_b32 m0, s46
	s_nop 0
	global_load_lds_dwordx4 v[220:221], off
	s_mov_b32 m0, s47
	s_nop 0
	global_load_lds_dwordx4 v[222:223], off
	s_waitcnt vmcnt(8)
	s_waitcnt lgkmcnt(0)
	s_barrier
	s_setprio 1
	s_waitcnt lgkmcnt(0)
	v_mfma_f32_16x16x32_bf16 v[60:63], v[128:131], v[176:179], v[60:63]
	v_mfma_f32_16x16x32_bf16 v[56:59], v[136:139], v[176:179], v[56:59]
	v_mfma_f32_16x16x32_bf16 v[44:47], v[128:131], v[192:195], v[44:47]
	v_mfma_f32_16x16x32_bf16 v[40:43], v[136:139], v[192:195], v[40:43]
	v_mfma_f32_16x16x32_bf16 v[28:31], v[128:131], v[200:203], v[28:31]
	v_mfma_f32_16x16x32_bf16 v[24:27], v[136:139], v[200:203], v[24:27]
	v_mfma_f32_16x16x32_bf16 v[12:15], v[128:131], v[208:211], v[12:15]
	v_mfma_f32_16x16x32_bf16 v[8:11], v[136:139], v[208:211], v[8:11]
	v_mfma_f32_16x16x32_bf16 v[60:63], v[132:135], v[180:183], v[60:63]
	v_mfma_f32_16x16x32_bf16 v[56:59], v[140:143], v[180:183], v[56:59]
	v_mfma_f32_16x16x32_bf16 v[44:47], v[132:135], v[196:199], v[44:47]
	v_mfma_f32_16x16x32_bf16 v[40:43], v[140:143], v[196:199], v[40:43]
	v_mfma_f32_16x16x32_bf16 v[28:31], v[132:135], v[204:207], v[28:31]
	v_mfma_f32_16x16x32_bf16 v[24:27], v[140:143], v[204:207], v[24:27]
	v_mfma_f32_16x16x32_bf16 v[12:15], v[132:135], v[212:215], v[12:15]
	v_mfma_f32_16x16x32_bf16 v[8:11], v[140:143], v[212:215], v[8:11]
	s_setprio 0
	s_setprio 1
	v_mfma_f32_16x16x32_bf16 v[52:55], v[144:147], v[176:179], v[52:55]
	v_mfma_f32_16x16x32_bf16 v[48:51], v[168:171], v[176:179], v[48:51]
	v_mfma_f32_16x16x32_bf16 v[36:39], v[144:147], v[192:195], v[36:39]
	v_mfma_f32_16x16x32_bf16 v[32:35], v[168:171], v[192:195], v[32:35]
	v_mfma_f32_16x16x32_bf16 v[20:23], v[144:147], v[200:203], v[20:23]
	v_mfma_f32_16x16x32_bf16 v[16:19], v[168:171], v[200:203], v[16:19]
	v_mfma_f32_16x16x32_bf16 v[4:7], v[144:147], v[208:211], v[4:7]
	v_mfma_f32_16x16x32_bf16 v[0:3], v[168:171], v[208:211], v[0:3]
	v_mfma_f32_16x16x32_bf16 v[52:55], v[148:151], v[180:183], v[52:55]
	v_mfma_f32_16x16x32_bf16 v[48:51], v[172:175], v[180:183], v[48:51]
	v_mfma_f32_16x16x32_bf16 v[36:39], v[148:151], v[196:199], v[36:39]
	v_mfma_f32_16x16x32_bf16 v[32:35], v[172:175], v[196:199], v[32:35]
	v_mfma_f32_16x16x32_bf16 v[20:23], v[148:151], v[204:207], v[20:23]
	v_mfma_f32_16x16x32_bf16 v[16:19], v[172:175], v[204:207], v[16:19]
	v_mfma_f32_16x16x32_bf16 v[4:7], v[148:151], v[212:215], v[4:7]
	v_mfma_f32_16x16x32_bf16 v[0:3], v[172:175], v[212:215], v[0:3]
	s_setprio 0
	s_barrier
	s_add_i32 s66, 0, 0x18000
	s_add_i32 s67, 0, 0x1c000
	v_add_u32_e32 v140, s66, v185
	v_add_u32_e32 v172, s67, v185
	ds_read_b128 v[128:131], v140
	ds_read_b128 v[132:135], v140 offset:1024
	ds_read_b128 v[136:139], v140 offset:2048
	ds_read_b128 v[140:143], v140 offset:3072
	ds_read_b128 v[144:147], v172
	ds_read_b128 v[148:151], v172 offset:1024
	ds_read_b128 v[168:171], v172 offset:2048
	ds_read_b128 v[172:175], v172 offset:3072
	s_add_u32 s38, s38, 0x40000
	s_addc_u32 s39, s39, 0
	s_mov_b32 m0, s48
	v_lshl_add_u64 v[224:225], s[38:39], 0, v[152:153]
	ds_read_b128 v[176:179], v189 offset:32768
	ds_read_b128 v[180:183], v189 offset:33792
	ds_read_b128 v[192:195], v189 offset:34816
	ds_read_b128 v[196:199], v189 offset:35840
	ds_read_b128 v[200:203], v189 offset:36864
	ds_read_b128 v[204:207], v189 offset:37888
	ds_read_b128 v[208:211], v189 offset:38912
	ds_read_b128 v[212:215], v189 offset:39936
	global_load_lds_dwordx4 v[224:225], off
	v_lshl_add_u64 v[224:225], s[38:39], 0, v[156:157]
	s_mov_b32 m0, s49
	s_nop 0
	global_load_lds_dwordx4 v[224:225], off
	s_waitcnt vmcnt(8)
	s_waitcnt lgkmcnt(0)
	s_barrier
	s_setprio 1
	s_waitcnt lgkmcnt(0)
	v_mfma_f32_16x16x32_bf16 v[124:127], v[128:131], v[176:179], v[124:127]
	v_mfma_f32_16x16x32_bf16 v[120:123], v[136:139], v[176:179], v[120:123]
	v_mfma_f32_16x16x32_bf16 v[108:111], v[128:131], v[192:195], v[108:111]
	v_mfma_f32_16x16x32_bf16 v[104:107], v[136:139], v[192:195], v[104:107]
	v_mfma_f32_16x16x32_bf16 v[92:95], v[128:131], v[200:203], v[92:95]
	v_mfma_f32_16x16x32_bf16 v[88:91], v[136:139], v[200:203], v[88:91]
	v_mfma_f32_16x16x32_bf16 v[76:79], v[128:131], v[208:211], v[76:79]
	v_mfma_f32_16x16x32_bf16 v[72:75], v[136:139], v[208:211], v[72:75]
	v_mfma_f32_16x16x32_bf16 v[124:127], v[132:135], v[180:183], v[124:127]
	v_mfma_f32_16x16x32_bf16 v[120:123], v[140:143], v[180:183], v[120:123]
	v_mfma_f32_16x16x32_bf16 v[108:111], v[132:135], v[196:199], v[108:111]
	v_mfma_f32_16x16x32_bf16 v[104:107], v[140:143], v[196:199], v[104:107]
	v_mfma_f32_16x16x32_bf16 v[92:95], v[132:135], v[204:207], v[92:95]
	v_mfma_f32_16x16x32_bf16 v[88:91], v[140:143], v[204:207], v[88:91]
	v_mfma_f32_16x16x32_bf16 v[76:79], v[132:135], v[212:215], v[76:79]
	v_mfma_f32_16x16x32_bf16 v[72:75], v[140:143], v[212:215], v[72:75]
	s_setprio 0
	s_setprio 1
	v_mfma_f32_16x16x32_bf16 v[116:119], v[144:147], v[176:179], v[116:119]
	v_mfma_f32_16x16x32_bf16 v[112:115], v[168:171], v[176:179], v[112:115]
	v_mfma_f32_16x16x32_bf16 v[100:103], v[144:147], v[192:195], v[100:103]
	v_mfma_f32_16x16x32_bf16 v[96:99], v[168:171], v[192:195], v[96:99]
	v_mfma_f32_16x16x32_bf16 v[84:87], v[144:147], v[200:203], v[84:87]
	v_mfma_f32_16x16x32_bf16 v[80:83], v[168:171], v[200:203], v[80:83]
	v_mfma_f32_16x16x32_bf16 v[68:71], v[144:147], v[208:211], v[68:71]
	v_mfma_f32_16x16x32_bf16 v[64:67], v[168:171], v[208:211], v[64:67]
	v_mfma_f32_16x16x32_bf16 v[116:119], v[148:151], v[180:183], v[116:119]
	v_mfma_f32_16x16x32_bf16 v[112:115], v[172:175], v[180:183], v[112:115]
	v_mfma_f32_16x16x32_bf16 v[100:103], v[148:151], v[196:199], v[100:103]
	v_mfma_f32_16x16x32_bf16 v[96:99], v[172:175], v[196:199], v[96:99]
	v_mfma_f32_16x16x32_bf16 v[84:87], v[148:151], v[204:207], v[84:87]
	v_mfma_f32_16x16x32_bf16 v[80:83], v[172:175], v[204:207], v[80:83]
	v_mfma_f32_16x16x32_bf16 v[68:71], v[148:151], v[212:215], v[68:71]
	v_mfma_f32_16x16x32_bf16 v[64:67], v[172:175], v[212:215], v[64:67]
	s_setprio 0
	s_barrier
	s_add_i32 s38, s66, s45
	v_lshl_add_u64 v[216:217], v[216:217], 0, s[6:7]
	s_mov_b32 m0, s38
	ds_read_b128 v[176:179], v189 offset:49152
	ds_read_b128 v[180:183], v189 offset:50176
	ds_read_b128 v[192:195], v189 offset:51200
	ds_read_b128 v[196:199], v189 offset:52224
	ds_read_b128 v[200:203], v189 offset:53248
	ds_read_b128 v[204:207], v189 offset:54272
	ds_read_b128 v[208:211], v189 offset:55296
	ds_read_b128 v[212:215], v189 offset:56320
	global_load_lds_dwordx4 v[216:217], off
	s_add_i32 m0, s38, 0x2000
	s_add_u32 s36, s36, 0x40080
	v_lshl_add_u64 v[216:217], v[218:219], 0, s[6:7]
	s_addc_u32 s37, s37, 0
	s_add_i32 s38, s67, s45
	global_load_lds_dwordx4 v[216:217], off
	v_lshl_add_u64 v[216:217], s[36:37], 0, v[154:155]
	s_mov_b32 m0, s38
	s_nop 0
	global_load_lds_dwordx4 v[216:217], off
	v_lshl_add_u64 v[216:217], s[36:37], 0, v[158:159]
	s_add_i32 m0, s38, 0x2000
	s_nop 0
	global_load_lds_dwordx4 v[216:217], off
	v_lshl_add_u64 v[216:217], v[220:221], 0, s[6:7]
	s_mov_b32 m0, s51
	s_nop 0
	global_load_lds_dwordx4 v[216:217], off
	v_lshl_add_u64 v[216:217], v[222:223], 0, s[6:7]
	s_mov_b32 m0, s52
	s_nop 0
	global_load_lds_dwordx4 v[216:217], off
	s_waitcnt vmcnt(8)
	s_waitcnt lgkmcnt(0)
	s_barrier
	s_setprio 1
	s_waitcnt lgkmcnt(0)
	v_mfma_f32_16x16x32_bf16 v[60:63], v[128:131], v[176:179], v[60:63]
	v_mfma_f32_16x16x32_bf16 v[56:59], v[136:139], v[176:179], v[56:59]
	v_mfma_f32_16x16x32_bf16 v[44:47], v[128:131], v[192:195], v[44:47]
	v_mfma_f32_16x16x32_bf16 v[40:43], v[136:139], v[192:195], v[40:43]
	v_mfma_f32_16x16x32_bf16 v[28:31], v[128:131], v[200:203], v[28:31]
	v_mfma_f32_16x16x32_bf16 v[24:27], v[136:139], v[200:203], v[24:27]
	v_mfma_f32_16x16x32_bf16 v[12:15], v[128:131], v[208:211], v[12:15]
	v_mfma_f32_16x16x32_bf16 v[8:11], v[136:139], v[208:211], v[8:11]
	v_mfma_f32_16x16x32_bf16 v[60:63], v[132:135], v[180:183], v[60:63]
	v_mfma_f32_16x16x32_bf16 v[56:59], v[140:143], v[180:183], v[56:59]
	v_mfma_f32_16x16x32_bf16 v[44:47], v[132:135], v[196:199], v[44:47]
	v_mfma_f32_16x16x32_bf16 v[40:43], v[140:143], v[196:199], v[40:43]
	v_mfma_f32_16x16x32_bf16 v[28:31], v[132:135], v[204:207], v[28:31]
	v_mfma_f32_16x16x32_bf16 v[24:27], v[140:143], v[204:207], v[24:27]
	v_mfma_f32_16x16x32_bf16 v[12:15], v[132:135], v[212:215], v[12:15]
	v_mfma_f32_16x16x32_bf16 v[8:11], v[140:143], v[212:215], v[8:11]
	s_setprio 0
	s_setprio 1
	v_mfma_f32_16x16x32_bf16 v[52:55], v[144:147], v[176:179], v[52:55]
	v_mfma_f32_16x16x32_bf16 v[48:51], v[168:171], v[176:179], v[48:51]
	v_mfma_f32_16x16x32_bf16 v[36:39], v[144:147], v[192:195], v[36:39]
	v_mfma_f32_16x16x32_bf16 v[32:35], v[168:171], v[192:195], v[32:35]
	v_mfma_f32_16x16x32_bf16 v[20:23], v[144:147], v[200:203], v[20:23]
	v_mfma_f32_16x16x32_bf16 v[16:19], v[168:171], v[200:203], v[16:19]
	v_mfma_f32_16x16x32_bf16 v[4:7], v[144:147], v[208:211], v[4:7]
	v_mfma_f32_16x16x32_bf16 v[0:3], v[168:171], v[208:211], v[0:3]
	v_mfma_f32_16x16x32_bf16 v[52:55], v[148:151], v[180:183], v[52:55]
	v_mfma_f32_16x16x32_bf16 v[48:51], v[172:175], v[180:183], v[48:51]
	v_mfma_f32_16x16x32_bf16 v[36:39], v[148:151], v[196:199], v[36:39]
	v_mfma_f32_16x16x32_bf16 v[32:35], v[172:175], v[196:199], v[32:35]
	v_mfma_f32_16x16x32_bf16 v[20:23], v[148:151], v[204:207], v[20:23]
	v_mfma_f32_16x16x32_bf16 v[16:19], v[172:175], v[204:207], v[16:19]
	v_mfma_f32_16x16x32_bf16 v[4:7], v[148:151], v[212:215], v[4:7]
	v_mfma_f32_16x16x32_bf16 v[0:3], v[172:175], v[212:215], v[0:3]
	s_setprio 0
	s_barrier
	s_add_i32 s65, s65, 2
	s_add_u32 s24, s24, 0x100
	s_addc_u32 s25, s25, 0
	s_add_u32 s63, s63, 0x100
	s_addc_u32 s64, s64, 0
	s_cmp_gt_u32 s65, 13
	s_cbranch_scc0 .LBB0_1530
	v_lshl_add_u32 v168, s60, 8, v184
	v_lshl_or_b32 v128, s8, 8, v186
	v_ashrrev_i32_e32 v169, 31, v168
	v_ashrrev_i32_e32 v129, 31, v128
	v_lshlrev_b64 v[130:131], 11, v[168:169]
	v_lshl_add_u64 v[130:131], s[34:35], 0, v[130:131]
	v_lshlrev_b64 v[170:171], 1, v[128:129]
	v_lshl_add_u64 v[200:201], v[130:131], 0, v[170:171]
	global_load_dwordx4 v[192:195], v[200:201], off
	global_load_dwordx4 v[196:199], v[200:201], off offset:256
	v_or_b32_e32 v180, 16, v168
	v_or_b32_e32 v176, 32, v168
	v_or_b32_e32 v172, 48, v168
	v_ashrrev_i32_e32 v181, 31, v180
	v_ashrrev_i32_e32 v177, 31, v176
	v_ashrrev_i32_e32 v173, 31, v172
	v_lshlrev_b64 v[128:129], 11, v[180:181]
	v_lshlrev_b64 v[130:131], 11, v[176:177]
	v_lshlrev_b64 v[132:133], 11, v[172:173]
	v_lshl_add_u64 v[128:129], s[34:35], 0, v[128:129]
	v_lshl_add_u64 v[130:131], s[34:35], 0, v[130:131]
	v_lshl_add_u64 v[132:133], s[34:35], 0, v[132:133]
	v_lshl_add_u64 v[182:183], v[128:129], 0, v[170:171]
	v_lshl_add_u64 v[178:179], v[130:131], 0, v[170:171]
	v_lshl_add_u64 v[174:175], v[132:133], 0, v[170:171]
	global_load_dwordx4 v[148:151], v[182:183], off
	global_load_dwordx4 v[144:147], v[182:183], off offset:256
	global_load_dwordx4 v[140:143], v[178:179], off
	global_load_dwordx4 v[136:139], v[178:179], off offset:256
	global_load_dwordx4 v[132:135], v[174:175], off
	global_load_dwordx4 v[128:131], v[174:175], off offset:256
	v_add_u32_e32 v224, 0x80, v168
	v_ashrrev_i32_e32 v225, 31, v224
	v_lshlrev_b64 v[224:225], 11, v[224:225]
	v_lshl_add_u64 v[224:225], s[34:35], 0, v[224:225]
	v_lshl_add_u64 v[212:213], v[224:225], 0, v[170:171]
	global_load_dwordx4 v[226:229], v[212:213], off
	global_load_dwordx4 v[230:233], v[212:213], off offset:256
	v_add_u32_e32 v224, 0x90, v168
	v_ashrrev_i32_e32 v225, 31, v224
	v_lshlrev_b64 v[224:225], 11, v[224:225]
	v_lshl_add_u64 v[224:225], s[34:35], 0, v[224:225]
	v_lshl_add_u64 v[214:215], v[224:225], 0, v[170:171]
	global_load_dwordx4 v[234:237], v[214:215], off
	global_load_dwordx4 v[238:241], v[214:215], off offset:256
	v_add_u32_e32 v224, 0xa0, v168
	v_ashrrev_i32_e32 v225, 31, v224
	v_lshlrev_b64 v[224:225], 11, v[224:225]
	v_lshl_add_u64 v[224:225], s[34:35], 0, v[224:225]
	v_lshl_add_u64 v[216:217], v[224:225], 0, v[170:171]
	global_load_dwordx4 v[242:245], v[216:217], off
	global_load_dwordx4 v[246:249], v[216:217], off offset:256
	v_add_u32_e32 v224, 0xb0, v168
	v_ashrrev_i32_e32 v225, 31, v224
	v_lshlrev_b64 v[224:225], 11, v[224:225]
	v_lshl_add_u64 v[224:225], s[34:35], 0, v[224:225]
	v_lshl_add_u64 v[218:219], v[224:225], 0, v[170:171]
	global_load_dwordx4 v[250:253], v[218:219], off
	global_load_dwordx4 v[220:223], v[218:219], off offset:256
	v_and_b32_e32 v202, 64, v190
	v_xor_b32_e32 v191, 16, v190
	v_add_u32_e32 v202, 64, v202
	v_xor_b32_e32 v203, 32, v190
	v_cmp_lt_i32_e32 vcc, v191, v202
	s_lshl_b32 s24, s8, 2
	s_ashr_i32 s25, s24, 31
	v_cndmask_b32_e32 v191, v190, v191, vcc
	v_cmp_lt_i32_e32 vcc, v203, v202
	v_lshlrev_b32_e32 v191, 2, v191
	s_waitcnt vmcnt(8)
	v_lshlrev_b32_e32 v202, 16, v192
	v_cndmask_b32_e32 v210, v190, v203, vcc
	v_and_b32_e32 v203, 0xffff0000, v192
	v_lshlrev_b32_e32 v192, 16, v193
	v_and_b32_e32 v193, 0xffff0000, v193
	v_lshlrev_b32_e32 v204, 16, v194
	v_and_b32_e32 v205, 0xffff0000, v194
	v_lshlrev_b32_e32 v194, 16, v195
	v_and_b32_e32 v195, 0xffff0000, v195
	v_lshlrev_b32_e32 v206, 16, v196
	v_and_b32_e32 v207, 0xffff0000, v196
	v_lshlrev_b32_e32 v196, 16, v197
	v_and_b32_e32 v197, 0xffff0000, v197
	v_lshlrev_b32_e32 v208, 16, v198
	v_and_b32_e32 v209, 0xffff0000, v198
	v_lshlrev_b32_e32 v198, 16, v199
	v_and_b32_e32 v199, 0xffff0000, v199
	v_pk_add_f32 v[126:127], v[126:127], v[192:193]
	v_pk_add_f32 v[124:125], v[124:125], v[202:203]
	v_pk_add_f32 v[122:123], v[122:123], v[194:195]
	v_pk_add_f32 v[120:121], v[120:121], v[204:205]
	v_pk_add_f32 v[118:119], v[118:119], v[196:197]
	v_pk_add_f32 v[116:117], v[116:117], v[206:207]
	v_pk_add_f32 v[192:193], v[114:115], v[198:199]
	v_pk_add_f32 v[194:195], v[112:113], v[208:209]
	v_cvt_pk_bf16_f32 v112, v124, v125
	v_cvt_pk_bf16_f32 v113, v126, v127
	v_mul_f32_e32 v114, v125, v125
	v_mul_f32_e32 v115, v127, v127
	v_mul_f32_e32 v125, v121, v121
	v_mul_f32_e32 v127, v123, v123
	v_mul_f32_e32 v196, v117, v117
	v_mul_f32_e32 v197, v119, v119
	v_mul_f32_e32 v198, v195, v195
	v_mul_f32_e32 v199, v193, v193
	v_fmac_f32_e32 v114, v124, v124
	v_fmac_f32_e32 v115, v126, v126
	v_fmac_f32_e32 v125, v120, v120
	v_fmac_f32_e32 v127, v122, v122
	v_fmac_f32_e32 v196, v116, v116
	v_fmac_f32_e32 v197, v118, v118
	v_fmac_f32_e32 v198, v194, v194
	v_fmac_f32_e32 v199, v192, v192
	v_add_f32_e32 v114, v114, v115
	v_add_f32_e32 v115, v125, v127
	v_add_f32_e32 v124, v196, v197
	v_add_f32_e32 v125, v198, v199
	v_add_f32_e32 v114, v114, v115
	v_add_f32_e32 v115, v124, v125
	v_add_f32_e32 v124, v114, v115
	ds_bpermute_b32 v125, v191, v124
	v_cvt_pk_bf16_f32 v114, v120, v121
	v_cvt_pk_bf16_f32 v115, v122, v123
	global_store_dwordx4 v[200:201], v[112:115], off
	v_cvt_pk_bf16_f32 v116, v116, v117
	v_cvt_pk_bf16_f32 v117, v118, v119
	s_waitcnt lgkmcnt(0)
	v_add_f32_e32 v113, v124, v125
	v_lshlrev_b32_e32 v112, 2, v210
	ds_bpermute_b32 v114, v112, v113
	v_cvt_pk_bf16_f32 v118, v194, v195
	v_cvt_pk_bf16_f32 v119, v192, v193
	global_store_dwordx4 v[200:201], v[116:119], off offset:256
	s_and_saveexec_b64 s[36:37], s[0:1]
	s_cbranch_execz .LBB0_1533
	s_waitcnt lgkmcnt(0)
	v_add_f32_e32 v113, v113, v114
	v_lshlrev_b64 v[114:115], 6, v[168:169]
	v_lshl_add_u64 v[114:115], s[74:75], 0, v[114:115]
	v_lshl_add_u64 v[114:115], s[24:25], 2, v[114:115]
	s_lshl_b32 s8, s50, 2
	v_lshl_add_u64 v[114:115], v[114:115], 0, s[8:9]
	global_store_dword v[114:115], v113, off

.LBB0_1539:
	s_or_b64 exec, exec, s[36:37]
	v_add_u32_e32 v100, 0x80, v168
	v_ashrrev_i32_e32 v101, 31, v100
	s_waitcnt lgkmcnt(0)
	v_lshlrev_b64 v[64:65], 11, v[100:101]
	v_lshl_add_u64 v[64:65], s[34:35], 0, v[64:65]
	v_lshl_add_u64 v[110:111], v[64:65], 0, v[170:171]
	s_waitcnt vmcnt(8)
	v_mov_b64_e32 v[102:103], v[226:227]
	v_mov_b64_e32 v[104:105], v[228:229]
	v_mov_b64_e32 v[106:107], v[230:231]
	v_mov_b64_e32 v[108:109], v[232:233]
	v_add_u32_e32 v96, 0x90, v168
	v_add_u32_e32 v92, 0xa0, v168
	v_add_u32_e32 v88, 0xb0, v168
	v_ashrrev_i32_e32 v97, 31, v96
	v_ashrrev_i32_e32 v93, 31, v92
	v_ashrrev_i32_e32 v89, 31, v88
	v_lshlrev_b64 v[64:65], 11, v[96:97]
	v_lshlrev_b64 v[66:67], 11, v[92:93]
	v_lshlrev_b64 v[68:69], 11, v[88:89]
	v_lshl_add_u64 v[64:65], s[34:35], 0, v[64:65]
	v_lshl_add_u64 v[66:67], s[34:35], 0, v[66:67]
	v_lshl_add_u64 v[68:69], s[34:35], 0, v[68:69]
	v_lshl_add_u64 v[98:99], v[64:65], 0, v[170:171]
	v_lshl_add_u64 v[94:95], v[66:67], 0, v[170:171]
	v_lshl_add_u64 v[90:91], v[68:69], 0, v[170:171]
	v_mov_b64_e32 v[84:85], v[234:235]
	v_mov_b64_e32 v[86:87], v[236:237]
	v_mov_b64_e32 v[80:81], v[238:239]
	v_mov_b64_e32 v[82:83], v[240:241]
	v_mov_b64_e32 v[76:77], v[242:243]
	v_mov_b64_e32 v[78:79], v[244:245]
	v_mov_b64_e32 v[72:73], v[246:247]
	v_mov_b64_e32 v[74:75], v[248:249]
	v_mov_b64_e32 v[68:69], v[250:251]
	v_mov_b64_e32 v[70:71], v[252:253]
	v_mov_b64_e32 v[64:65], v[220:221]
	v_mov_b64_e32 v[66:67], v[222:223]
	s_nop 0
	v_lshlrev_b32_e32 v114, 16, v102
	v_and_b32_e32 v115, 0xffff0000, v102
	v_lshlrev_b32_e32 v102, 16, v103
	v_and_b32_e32 v103, 0xffff0000, v103
	v_lshlrev_b32_e32 v116, 16, v104
	v_and_b32_e32 v117, 0xffff0000, v104
	v_lshlrev_b32_e32 v104, 16, v105
	v_and_b32_e32 v105, 0xffff0000, v105
	s_nop 0
	v_lshlrev_b32_e32 v118, 16, v106
	v_and_b32_e32 v119, 0xffff0000, v106
	v_lshlrev_b32_e32 v106, 16, v107
	v_and_b32_e32 v107, 0xffff0000, v107
	v_lshlrev_b32_e32 v120, 16, v108
	v_and_b32_e32 v121, 0xffff0000, v108
	v_lshlrev_b32_e32 v108, 16, v109
	v_and_b32_e32 v109, 0xffff0000, v109
	v_pk_add_f32 v[62:63], v[62:63], v[102:103]
	v_pk_add_f32 v[60:61], v[60:61], v[114:115]
	v_pk_add_f32 v[58:59], v[58:59], v[104:105]
	v_pk_add_f32 v[56:57], v[56:57], v[116:117]
	v_pk_add_f32 v[54:55], v[54:55], v[106:107]
	v_pk_add_f32 v[52:53], v[52:53], v[118:119]
	v_pk_add_f32 v[102:103], v[50:51], v[108:109]
	v_pk_add_f32 v[104:105], v[48:49], v[120:121]
	v_cvt_pk_bf16_f32 v48, v60, v61
	v_cvt_pk_bf16_f32 v49, v62, v63
	v_mul_f32_e32 v50, v61, v61
	v_mul_f32_e32 v51, v63, v63
	v_mul_f32_e32 v61, v57, v57
	v_mul_f32_e32 v63, v59, v59
	v_mul_f32_e32 v106, v53, v53
	v_mul_f32_e32 v107, v55, v55
	v_mul_f32_e32 v108, v105, v105
	v_mul_f32_e32 v109, v103, v103
	v_fmac_f32_e32 v50, v60, v60
	v_fmac_f32_e32 v51, v62, v62
	v_fmac_f32_e32 v61, v56, v56
	v_fmac_f32_e32 v63, v58, v58
	v_fmac_f32_e32 v106, v52, v52
	v_fmac_f32_e32 v107, v54, v54
	v_fmac_f32_e32 v108, v104, v104
	v_fmac_f32_e32 v109, v102, v102
	v_add_f32_e32 v50, v50, v51
	v_add_f32_e32 v51, v61, v63
	v_add_f32_e32 v60, v106, v107
	v_add_f32_e32 v61, v108, v109
	v_add_f32_e32 v50, v50, v51
	v_add_f32_e32 v51, v60, v61
	v_add_f32_e32 v60, v50, v51
	ds_bpermute_b32 v61, v191, v60
	v_cvt_pk_bf16_f32 v50, v56, v57
	v_cvt_pk_bf16_f32 v51, v58, v59
	global_store_dwordx4 v[110:111], v[48:51], off
	s_waitcnt lgkmcnt(0)
	s_nop 0
	v_add_f32_e32 v48, v60, v61
	ds_bpermute_b32 v49, v112, v48
	v_cvt_pk_bf16_f32 v50, v52, v53
	v_cvt_pk_bf16_f32 v51, v54, v55
	v_cvt_pk_bf16_f32 v52, v104, v105
	v_cvt_pk_bf16_f32 v53, v102, v103
	global_store_dwordx4 v[110:111], v[50:53], off offset:256
	s_and_saveexec_b64 s[36:37], s[0:1]
	s_cbranch_execz .LBB0_1541
	s_waitcnt lgkmcnt(0)
	v_add_f32_e32 v50, v48, v49
	v_lshlrev_b64 v[48:49], 6, v[100:101]
	v_lshl_add_u64 v[48:49], s[74:75], 0, v[48:49]
	v_lshl_add_u64 v[48:49], s[24:25], 2, v[48:49]
	s_lshl_b32 s8, s50, 2
	v_lshl_add_u64 v[48:49], v[48:49], 0, s[8:9]
	global_store_dword v[48:49], v50, off
.LBB0_1541:
	s_or_b64 exec, exec, s[36:37]
	s_nop 0
	v_lshlrev_b32_e32 v48, 16, v84
	s_waitcnt lgkmcnt(0)
	v_and_b32_e32 v49, 0xffff0000, v84
	v_lshlrev_b32_e32 v50, 16, v85
	v_and_b32_e32 v51, 0xffff0000, v85
	v_lshlrev_b32_e32 v52, 16, v86
	v_and_b32_e32 v53, 0xffff0000, v86
	v_lshlrev_b32_e32 v54, 16, v87
	v_and_b32_e32 v55, 0xffff0000, v87
	s_nop 0
	v_lshlrev_b32_e32 v60, 16, v82
	v_and_b32_e32 v61, 0xffff0000, v82
	v_pk_add_f32 v[46:47], v[46:47], v[50:51]
	v_pk_add_f32 v[44:45], v[44:45], v[48:49]
	v_pk_add_f32 v[48:49], v[42:43], v[54:55]
	v_pk_add_f32 v[42:43], v[40:41], v[52:53]
	v_pk_add_f32 v[52:53], v[32:33], v[60:61]
	v_mul_f32_e32 v32, v45, v45
	v_mul_f32_e32 v33, v47, v47
	v_lshlrev_b32_e32 v62, 16, v83
	v_and_b32_e32 v63, 0xffff0000, v83
	v_fmac_f32_e32 v32, v44, v44
	v_fmac_f32_e32 v33, v46, v46
	v_pk_add_f32 v[50:51], v[34:35], v[62:63]
	v_add_f32_e32 v32, v32, v33
	v_mul_f32_e32 v33, v43, v43
	v_mul_f32_e32 v34, v49, v49
	v_lshlrev_b32_e32 v56, 16, v80
	v_and_b32_e32 v57, 0xffff0000, v80
	v_lshlrev_b32_e32 v58, 16, v81
	v_and_b32_e32 v59, 0xffff0000, v81
	v_fmac_f32_e32 v33, v42, v42
	v_fmac_f32_e32 v34, v48, v48
	v_pk_add_f32 v[38:39], v[38:39], v[58:59]
	v_pk_add_f32 v[36:37], v[36:37], v[56:57]
	v_add_f32_e32 v33, v33, v34
	v_add_f32_e32 v32, v32, v33
	v_mul_f32_e32 v33, v37, v37
	v_mul_f32_e32 v34, v39, v39
	v_fmac_f32_e32 v33, v36, v36
	v_fmac_f32_e32 v34, v38, v38
	v_add_f32_e32 v33, v33, v34
	v_mul_f32_e32 v34, v53, v53
	v_mul_f32_e32 v35, v51, v51
	v_fmac_f32_e32 v34, v52, v52
	v_fmac_f32_e32 v35, v50, v50
	v_add_f32_e32 v34, v34, v35
	v_add_f32_e32 v33, v33, v34
	v_add_f32_e32 v32, v32, v33
	ds_bpermute_b32 v33, v191, v32
	v_cvt_pk_bf16_f32 v40, v44, v45
	v_cvt_pk_bf16_f32 v41, v46, v47
	v_cvt_pk_bf16_f32 v42, v42, v43
	v_cvt_pk_bf16_f32 v43, v48, v49
	s_waitcnt lgkmcnt(0)
	v_add_f32_e32 v32, v32, v33
	ds_bpermute_b32 v33, v112, v32
	v_cvt_pk_bf16_f32 v34, v36, v37
	v_cvt_pk_bf16_f32 v35, v38, v39
	v_cvt_pk_bf16_f32 v36, v52, v53
	v_cvt_pk_bf16_f32 v37, v50, v51
	global_store_dwordx4 v[98:99], v[40:43], off
	global_store_dwordx4 v[98:99], v[34:37], off offset:256
	s_and_saveexec_b64 s[36:37], s[0:1]
	s_cbranch_execz .LBB0_1543
	s_waitcnt lgkmcnt(0)
	v_add_f32_e32 v34, v32, v33
	v_lshlrev_b64 v[32:33], 6, v[96:97]
	v_lshl_add_u64 v[32:33], s[74:75], 0, v[32:33]
	v_lshl_add_u64 v[32:33], s[24:25], 2, v[32:33]
	s_lshl_b32 s8, s50, 2
	v_lshl_add_u64 v[32:33], v[32:33], 0, s[8:9]
	global_store_dword v[32:33], v34, off
.LBB0_1543:
	s_or_b64 exec, exec, s[36:37]
	s_nop 0
	v_lshlrev_b32_e32 v32, 16, v76
	s_waitcnt lgkmcnt(0)
	v_and_b32_e32 v33, 0xffff0000, v76
	v_lshlrev_b32_e32 v34, 16, v77
	v_and_b32_e32 v35, 0xffff0000, v77
	v_lshlrev_b32_e32 v36, 16, v78
	v_and_b32_e32 v37, 0xffff0000, v78
	v_lshlrev_b32_e32 v38, 16, v79
	v_and_b32_e32 v39, 0xffff0000, v79
	s_nop 0
	v_lshlrev_b32_e32 v44, 16, v74
	v_and_b32_e32 v45, 0xffff0000, v74
	v_pk_add_f32 v[30:31], v[30:31], v[34:35]
	v_pk_add_f32 v[28:29], v[28:29], v[32:33]
	v_pk_add_f32 v[32:33], v[26:27], v[38:39]
	v_pk_add_f32 v[26:27], v[24:25], v[36:37]
	v_pk_add_f32 v[36:37], v[16:17], v[44:45]
	v_mul_f32_e32 v16, v29, v29
	v_mul_f32_e32 v17, v31, v31
	v_lshlrev_b32_e32 v46, 16, v75
	v_and_b32_e32 v47, 0xffff0000, v75
	v_fmac_f32_e32 v16, v28, v28
	v_fmac_f32_e32 v17, v30, v30
	v_pk_add_f32 v[34:35], v[18:19], v[46:47]
	v_add_f32_e32 v16, v16, v17
	v_mul_f32_e32 v17, v27, v27
	v_mul_f32_e32 v18, v33, v33
	v_lshlrev_b32_e32 v40, 16, v72
	v_and_b32_e32 v41, 0xffff0000, v72
	v_lshlrev_b32_e32 v42, 16, v73
	v_and_b32_e32 v43, 0xffff0000, v73
	v_fmac_f32_e32 v17, v26, v26
	v_fmac_f32_e32 v18, v32, v32
	v_pk_add_f32 v[22:23], v[22:23], v[42:43]
	v_pk_add_f32 v[20:21], v[20:21], v[40:41]
	v_add_f32_e32 v17, v17, v18
	v_add_f32_e32 v16, v16, v17
	v_mul_f32_e32 v17, v21, v21
	v_mul_f32_e32 v18, v23, v23
	v_fmac_f32_e32 v17, v20, v20
	v_fmac_f32_e32 v18, v22, v22
	v_add_f32_e32 v17, v17, v18
	v_mul_f32_e32 v18, v37, v37
	v_mul_f32_e32 v19, v35, v35
	v_fmac_f32_e32 v18, v36, v36
	v_fmac_f32_e32 v19, v34, v34
	v_add_f32_e32 v18, v18, v19
	v_add_f32_e32 v17, v17, v18
	v_add_f32_e32 v16, v16, v17
	ds_bpermute_b32 v17, v191, v16
	v_cvt_pk_bf16_f32 v24, v28, v29
	v_cvt_pk_bf16_f32 v25, v30, v31
	v_cvt_pk_bf16_f32 v26, v26, v27
	v_cvt_pk_bf16_f32 v27, v32, v33
	s_waitcnt lgkmcnt(0)
	v_add_f32_e32 v16, v16, v17
	ds_bpermute_b32 v17, v112, v16
	v_cvt_pk_bf16_f32 v18, v20, v21
	v_cvt_pk_bf16_f32 v19, v22, v23
	v_cvt_pk_bf16_f32 v20, v36, v37
	v_cvt_pk_bf16_f32 v21, v34, v35
	global_store_dwordx4 v[94:95], v[24:27], off
	global_store_dwordx4 v[94:95], v[18:21], off offset:256
	s_and_saveexec_b64 s[36:37], s[0:1]
	s_cbranch_execz .LBB0_1545
	s_waitcnt lgkmcnt(0)
	v_add_f32_e32 v18, v16, v17
	v_lshlrev_b64 v[16:17], 6, v[92:93]
	v_lshl_add_u64 v[16:17], s[74:75], 0, v[16:17]
	v_lshl_add_u64 v[16:17], s[24:25], 2, v[16:17]
	s_lshl_b32 s8, s50, 2
	v_lshl_add_u64 v[16:17], v[16:17], 0, s[8:9]
	global_store_dword v[16:17], v18, off
.LBB0_1545:
	s_or_b64 exec, exec, s[36:37]
	s_nop 0
	v_lshlrev_b32_e32 v16, 16, v68
	s_waitcnt lgkmcnt(0)
	v_and_b32_e32 v17, 0xffff0000, v68
	v_lshlrev_b32_e32 v18, 16, v69
	v_and_b32_e32 v19, 0xffff0000, v69
	v_lshlrev_b32_e32 v20, 16, v70
	v_and_b32_e32 v21, 0xffff0000, v70
	v_lshlrev_b32_e32 v22, 16, v71
	v_and_b32_e32 v23, 0xffff0000, v71
	s_nop 0
	v_lshlrev_b32_e32 v28, 16, v66
	v_and_b32_e32 v29, 0xffff0000, v66
	v_pk_add_f32 v[14:15], v[14:15], v[18:19]
	v_pk_add_f32 v[12:13], v[12:13], v[16:17]
	v_pk_add_f32 v[16:17], v[10:11], v[22:23]
	v_pk_add_f32 v[10:11], v[8:9], v[20:21]
	v_pk_add_f32 v[20:21], v[0:1], v[28:29]
	v_mul_f32_e32 v0, v13, v13
	v_mul_f32_e32 v1, v15, v15
	v_lshlrev_b32_e32 v30, 16, v67
	v_and_b32_e32 v31, 0xffff0000, v67
	v_fmac_f32_e32 v0, v12, v12
	v_fmac_f32_e32 v1, v14, v14
	v_pk_add_f32 v[18:19], v[2:3], v[30:31]
	v_add_f32_e32 v0, v0, v1
	v_mul_f32_e32 v1, v11, v11
	v_mul_f32_e32 v2, v17, v17
	v_lshlrev_b32_e32 v24, 16, v64
	v_and_b32_e32 v25, 0xffff0000, v64
	v_lshlrev_b32_e32 v26, 16, v65
	v_and_b32_e32 v27, 0xffff0000, v65
	v_fmac_f32_e32 v1, v10, v10
	v_fmac_f32_e32 v2, v16, v16
	v_pk_add_f32 v[6:7], v[6:7], v[26:27]
	v_pk_add_f32 v[4:5], v[4:5], v[24:25]
	v_add_f32_e32 v1, v1, v2
	v_add_f32_e32 v0, v0, v1
	v_mul_f32_e32 v1, v5, v5
	v_mul_f32_e32 v2, v7, v7
	v_fmac_f32_e32 v1, v4, v4
	v_fmac_f32_e32 v2, v6, v6
	v_add_f32_e32 v1, v1, v2
	v_mul_f32_e32 v2, v21, v21
	v_mul_f32_e32 v3, v19, v19
	v_fmac_f32_e32 v2, v20, v20
	v_fmac_f32_e32 v3, v18, v18
	v_add_f32_e32 v2, v2, v3
	v_add_f32_e32 v1, v1, v2
	v_add_f32_e32 v0, v0, v1
	ds_bpermute_b32 v1, v191, v0
	v_cvt_pk_bf16_f32 v8, v12, v13
	v_cvt_pk_bf16_f32 v9, v14, v15
	v_cvt_pk_bf16_f32 v10, v10, v11
	v_cvt_pk_bf16_f32 v11, v16, v17
	s_waitcnt lgkmcnt(0)
	v_add_f32_e32 v0, v0, v1
	ds_bpermute_b32 v1, v112, v0
	v_cvt_pk_bf16_f32 v2, v4, v5
	v_cvt_pk_bf16_f32 v3, v6, v7
	v_cvt_pk_bf16_f32 v4, v20, v21
	v_cvt_pk_bf16_f32 v5, v18, v19
	global_store_dwordx4 v[90:91], v[8:11], off
	global_store_dwordx4 v[90:91], v[2:5], off offset:256
	s_and_saveexec_b64 s[36:37], s[0:1]
	s_cbranch_execz .LBB0_1522
	s_waitcnt lgkmcnt(0)
	v_add_f32_e32 v2, v0, v1
	v_lshlrev_b64 v[0:1], 6, v[88:89]
	v_lshl_add_u64 v[0:1], s[74:75], 0, v[0:1]
	v_lshl_add_u64 v[0:1], s[24:25], 2, v[0:1]
	s_lshl_b32 s8, s50, 2
	v_lshl_add_u64 v[0:1], v[0:1], 0, s[8:9]
	global_store_dword v[0:1], v2, off
	s_branch .LBB0_1522
